# epilogue load hoisting in P3-final (16 gate loads up front), P4 (rolling depth-8 x loads) and P6 (16 x1b loads up front)
# baseline (speedup 1.0000x reference)
; __device__ __forceinline__ float bf_lo(unsigned w) { return __uint_as_float(w << 16); }
; __device__ __forceinline__ float bf_hi(unsigned w) { return __uint_as_float(w & 0xffff0000u); }
; __device__ __forceinline__ float sigm(float x) { return __builtin_amdgcn_rcpf(1.0f + __builtin_amdgcn_exp2f(-1.4426950408889634f * x)); }
; __device__ __forceinline__ u32x4 pack8(f32x4 a, f32x4 b) { u32x4 w; w.x = cvt_pk_bf16(a[0], a[1]); w.y = cvt_pk_bf16(a[2], a[3]); w.z = cvt_pk_bf16(b[0], b[1]); w.w = cvt_pk_bf16(b[2], b[3]); return w; }
;     __device__ __forceinline__ void operator()(const f32x4 (&acc)[2][2][4][2], const Unit& u, int wr, int wc, int fr, int fq) const {
;         const int row0 = u.pm * BM + wr * 64 + fr, col0 = u.pn * BM + wc * 32 + 8 * fq;
; #pragma unroll
;         for (int ai = 0; ai < 2; ++ai)
; #pragma unroll
;             for (int m = 0; m < 4; ++m) { const size_t ro = (size_t)(row0 + ai * HALF + m * 16) * 1024 + col0;
; #pragma unroll
;                 for (int bj = 0; bj < 2; ++bj) { const size_t o = ro + bj * HALF; const u32x4 b = *(const u32x4*)(GBr + o);
;                     f32x4 s0, s1; s0[0] = sigm(fmaxf(bf_lo(b.x), -30.f)); s0[1] = sigm(fmaxf(bf_hi(b.x), -30.f)); s0[2] = sigm(fmaxf(bf_lo(b.y), -30.f)); s0[3] = sigm(fmaxf(bf_hi(b.y), -30.f));
;                     s1[0] = sigm(fmaxf(bf_lo(b.z), -30.f)); s1[1] = sigm(fmaxf(bf_hi(b.z), -30.f)); s1[2] = sigm(fmaxf(bf_lo(b.w), -30.f)); s1[3] = sigm(fmaxf(bf_hi(b.w), -30.f));
;                     *(u32x4*)(Mx + o) = pack8(s0 * acc[ai][bj][m][0], s1 * acc[ai][bj][m][1]); } }
.LBB0_1032:
	v_lshl_add_u32 v2, s56, 8, v179
	v_ashrrev_i32_e32 v3, 31, v2
	v_lshl_or_b32 v168, s0, 8, v181
	v_lshlrev_b64 v[132:133], 10, v[2:3]
	v_ashrrev_i32_e32 v169, 31, v168
	s_cmp_lg_u32 s1, 0
	v_lshl_add_u64 v[132:133], v[132:133], 0, v[168:169]
	s_cselect_b64 s[54:55], -1, 0
	v_lshlrev_b64 v[142:143], 1, v[132:133]
	v_or_b32_e32 v172, 16, v2
	v_or_b32_e32 v170, 32, v2
	s_and_b64 vcc, exec, s[54:55]
	v_lshl_add_u64 v[132:133], s[6:7], 0, v[142:143]
	v_or_b32_e32 v140, 0x100, v142
	v_ashrrev_i32_e32 v173, 31, v172
	v_ashrrev_i32_e32 v171, 31, v170
	s_cbranch_vccz .LBB0_1040
	v_mov_b32_e32 v228, v132
	v_mov_b32_e32 v229, v133
	s_mov_b32 s98, 0x8000
	s_mov_b32 s99, 0
	global_load_dwordx4 v[184:187], v[228:229], off
	global_load_dwordx4 v[188:191], v[228:229], off offset:256
	v_lshl_add_u64 v[228:229], v[228:229], 0, s[98:99]
	global_load_dwordx4 v[192:195], v[228:229], off
	global_load_dwordx4 v[196:199], v[228:229], off offset:256
	v_lshl_add_u64 v[228:229], v[228:229], 0, s[98:99]
	global_load_dwordx4 v[200:203], v[228:229], off
	global_load_dwordx4 v[204:207], v[228:229], off offset:256
	v_lshl_add_u64 v[228:229], v[228:229], 0, s[98:99]
	global_load_dwordx4 v[208:211], v[228:229], off
	global_load_dwordx4 v[212:215], v[228:229], off offset:256
	v_lshl_add_u64 v[228:229], v[228:229], 0, s[98:99]
	v_lshl_add_u64 v[228:229], v[228:229], 0, s[98:99]
	v_lshl_add_u64 v[228:229], v[228:229], 0, s[98:99]
	v_lshl_add_u64 v[228:229], v[228:229], 0, s[98:99]
	v_lshl_add_u64 v[228:229], v[228:229], 0, s[98:99]
	global_load_dwordx4 v[216:219], v[228:229], off
	global_load_dwordx4 v[220:223], v[228:229], off offset:256
	v_lshl_add_u64 v[228:229], v[228:229], 0, s[98:99]
	global_load_dwordx4 v[224:227], v[228:229], off
	global_load_dwordx4 v[238:241], v[228:229], off offset:256
	v_lshl_add_u64 v[228:229], v[228:229], 0, s[98:99]
	global_load_dwordx4 v[242:245], v[228:229], off
	global_load_dwordx4 v[246:249], v[228:229], off offset:256
	v_lshl_add_u64 v[228:229], v[228:229], 0, s[98:99]
	global_load_dwordx4 v[252:255], v[228:229], off
	v_lshl_add_u64 v[138:139], s[16:17], 0, v[142:143]
	v_mov_b32_e32 v141, v143
	v_lshl_add_u64 v[144:145], s[6:7], 0, v[140:141]
	s_waitcnt vmcnt(0)
	v_lshlrev_b32_e32 v1, 16, v184
	v_and_b32_e32 v134, 0xffff0000, v184
	v_lshlrev_b32_e32 v146, 16, v185
	v_and_b32_e32 v135, 0xffff0000, v185
	v_lshlrev_b32_e32 v147, 16, v186
	v_and_b32_e32 v136, 0xffff0000, v186
	v_lshlrev_b32_e32 v148, 16, v187
	v_and_b32_e32 v137, 0xffff0000, v187
	global_load_dwordx4 v[184:187], v[228:229], off offset:256
	v_max_f32_e32 v1, v1, v1
	v_max_f32_e32 v134, v134, v134
	v_max_f32_e32 v146, v146, v146
	v_max_f32_e32 v135, v135, v135
	v_max_f32_e32 v147, v147, v147
	v_max_f32_e32 v136, v136, v136
	v_max_f32_e32 v148, v148, v148
	v_max_f32_e32 v137, v137, v137
	v_max_f32_e32 v1, 0xc1f00000, v1
	v_max_f32_e32 v134, 0xc1f00000, v134
	v_max_f32_e32 v146, 0xc1f00000, v146
	v_max_f32_e32 v135, 0xc1f00000, v135
	v_max_f32_e32 v147, 0xc1f00000, v147
	v_max_f32_e32 v136, 0xc1f00000, v136
	v_max_f32_e32 v148, 0xc1f00000, v148
	v_max_f32_e32 v137, 0xc1f00000, v137
	v_mul_f32_e32 v1, 0xbfb8aa3b, v1
	v_mul_f32_e32 v134, 0xbfb8aa3b, v134
	v_mul_f32_e32 v146, 0xbfb8aa3b, v146
	v_mul_f32_e32 v135, 0xbfb8aa3b, v135
	v_mul_f32_e32 v147, 0xbfb8aa3b, v147
	v_mul_f32_e32 v136, 0xbfb8aa3b, v136
	v_mul_f32_e32 v148, 0xbfb8aa3b, v148
	v_mul_f32_e32 v137, 0xbfb8aa3b, v137
	v_exp_f32_e32 v1, v1
	v_exp_f32_e32 v134, v134
	v_exp_f32_e32 v146, v146
	v_exp_f32_e32 v135, v135
	v_exp_f32_e32 v147, v147
	v_exp_f32_e32 v136, v136
	v_exp_f32_e32 v148, v148
	v_exp_f32_e32 v137, v137
	v_add_f32_e32 v1, 1.0, v1
	v_add_f32_e32 v149, 1.0, v134
	v_add_f32_e32 v146, 1.0, v146
	v_add_f32_e32 v150, 1.0, v135
	v_add_f32_e32 v147, 1.0, v147
	v_add_f32_e32 v151, 1.0, v136
	v_add_f32_e32 v148, 1.0, v148
	v_add_f32_e32 v174, 1.0, v137
	v_rcp_f32_e32 v134, v1
	v_rcp_f32_e32 v135, v149
	v_rcp_f32_e32 v136, v146
	v_rcp_f32_e32 v137, v150
	v_rcp_f32_e32 v146, v147
	v_rcp_f32_e32 v148, v148
	v_rcp_f32_e32 v149, v174
	v_rcp_f32_e32 v147, v151
	v_pk_mul_f32 v[136:137], v[130:131], v[136:137]
	v_pk_mul_f32 v[134:135], v[128:129], v[134:135]
	v_pk_mul_f32 v[148:149], v[126:127], v[148:149]
	v_pk_mul_f32 v[146:147], v[124:125], v[146:147]
	v_cvt_pk_bf16_f32 v134, v134, v135
	v_cvt_pk_bf16_f32 v135, v136, v137
	s_nop 0
	v_cvt_pk_bf16_f32 v136, v146, v147
	v_cvt_pk_bf16_f32 v137, v148, v149
	global_store_dwordx4 v[138:139], v[134:137], off
	v_lshl_add_u64 v[138:139], s[16:17], 0, v[140:141]
	v_lshlrev_b64 v[134:135], 10, v[172:173]
	v_lshl_add_u64 v[134:135], v[134:135], 0, v[168:169]
	v_lshlrev_b64 v[136:137], 1, v[134:135]
	v_lshl_add_u64 v[134:135], s[6:7], 0, v[136:137]
	s_waitcnt vmcnt(0)
; __device__ __forceinline__ float bf_lo(unsigned w) { return __uint_as_float(w << 16); }
; __device__ __forceinline__ float bf_hi(unsigned w) { return __uint_as_float(w & 0xffff0000u); }
; __device__ __forceinline__ float sigm(float x) { return __builtin_amdgcn_rcpf(1.0f + __builtin_amdgcn_exp2f(-1.4426950408889634f * x)); }
; __device__ __forceinline__ u32x4 pack8(f32x4 a, f32x4 b) { u32x4 w; w.x = cvt_pk_bf16(a[0], a[1]); w.y = cvt_pk_bf16(a[2], a[3]); w.z = cvt_pk_bf16(b[0], b[1]); w.w = cvt_pk_bf16(b[2], b[3]); return w; }
;     __device__ __forceinline__ void operator()(const f32x4 (&acc)[2][2][4][2], const Unit& u, int wr, int wc, int fr, int fq) const {
;     ...
;                 for (int bj = 0; bj < 2; ++bj) { const size_t o = ro + bj * HALF; const u32x4 b = *(const u32x4*)(GBr + o);
;                     f32x4 s0, s1; s0[0] = sigm(fmaxf(bf_lo(b.x), -30.f)); s0[1] = sigm(fmaxf(bf_hi(b.x), -30.f)); s0[2] = sigm(fmaxf(bf_lo(b.y), -30.f)); s0[3] = sigm(fmaxf(bf_hi(b.y), -30.f));
;                     s1[0] = sigm(fmaxf(bf_lo(b.z), -30.f)); s1[1] = sigm(fmaxf(bf_hi(b.z), -30.f)); s1[2] = sigm(fmaxf(bf_lo(b.w), -30.f)); s1[3] = sigm(fmaxf(bf_hi(b.w), -30.f));
;                     *(u32x4*)(Mx + o) = pack8(s0 * acc[ai][bj][m][0], s1 * acc[ai][bj][m][1]); } }
	v_lshlrev_b32_e32 v1, 16, v188
	v_and_b32_e32 v141, 0xffff0000, v188
	v_lshlrev_b32_e32 v144, 16, v189
	v_and_b32_e32 v145, 0xffff0000, v189
	v_lshlrev_b32_e32 v148, 16, v190
	v_and_b32_e32 v146, 0xffff0000, v190
	v_lshlrev_b32_e32 v149, 16, v191
	v_and_b32_e32 v147, 0xffff0000, v191
	v_max_f32_e32 v1, v1, v1
	v_max_f32_e32 v141, v141, v141
	v_max_f32_e32 v144, v144, v144
	v_max_f32_e32 v145, v145, v145
	v_max_f32_e32 v148, v148, v148
	v_max_f32_e32 v146, v146, v146
	v_max_f32_e32 v149, v149, v149
	v_max_f32_e32 v147, v147, v147
	v_max_f32_e32 v1, 0xc1f00000, v1
	v_max_f32_e32 v141, 0xc1f00000, v141
	v_max_f32_e32 v144, 0xc1f00000, v144
	v_max_f32_e32 v145, 0xc1f00000, v145
	v_max_f32_e32 v148, 0xc1f00000, v148
	v_max_f32_e32 v146, 0xc1f00000, v146
	v_max_f32_e32 v149, 0xc1f00000, v149
	v_max_f32_e32 v147, 0xc1f00000, v147
	v_mul_f32_e32 v1, 0xbfb8aa3b, v1
	v_mul_f32_e32 v141, 0xbfb8aa3b, v141
	v_mul_f32_e32 v144, 0xbfb8aa3b, v144
	v_mul_f32_e32 v145, 0xbfb8aa3b, v145
	v_mul_f32_e32 v148, 0xbfb8aa3b, v148
	v_mul_f32_e32 v146, 0xbfb8aa3b, v146
	v_mul_f32_e32 v149, 0xbfb8aa3b, v149
	v_mul_f32_e32 v147, 0xbfb8aa3b, v147
	v_exp_f32_e32 v1, v1
	v_exp_f32_e32 v141, v141
	v_exp_f32_e32 v144, v144
	v_exp_f32_e32 v145, v145
	v_exp_f32_e32 v148, v148
	v_exp_f32_e32 v146, v146
	v_exp_f32_e32 v149, v149
	v_exp_f32_e32 v147, v147
	v_add_f32_e32 v1, 1.0, v1
	v_add_f32_e32 v141, 1.0, v141
	v_add_f32_e32 v150, 1.0, v144
	v_add_f32_e32 v151, 1.0, v145
	v_add_f32_e32 v148, 1.0, v148
	v_add_f32_e32 v174, 1.0, v146
	v_add_f32_e32 v149, 1.0, v149
	v_add_f32_e32 v175, 1.0, v147
	v_rcp_f32_e32 v144, v1
	v_rcp_f32_e32 v145, v141
	v_rcp_f32_e32 v146, v150
	v_rcp_f32_e32 v147, v151
	v_rcp_f32_e32 v148, v148
	v_rcp_f32_e32 v150, v149
	v_rcp_f32_e32 v151, v175
	v_rcp_f32_e32 v149, v174
	v_pk_mul_f32 v[146:147], v[98:99], v[146:147]
	v_pk_mul_f32 v[144:145], v[96:97], v[144:145]
	v_pk_mul_f32 v[150:151], v[94:95], v[150:151]
	v_pk_mul_f32 v[148:149], v[92:93], v[148:149]
	v_cvt_pk_bf16_f32 v144, v144, v145
	v_cvt_pk_bf16_f32 v145, v146, v147
	s_nop 0
	v_cvt_pk_bf16_f32 v146, v148, v149
	v_cvt_pk_bf16_f32 v147, v150, v151
	global_store_dwordx4 v[138:139], v[144:147], off
	v_lshl_add_u64 v[134:135], s[16:17], 0, v[136:137]
	v_or_b32_e32 v136, 0x100, v136
	v_lshl_add_u64 v[138:139], s[6:7], 0, v[136:137]
	s_waitcnt vmcnt(0)
	v_lshlrev_b32_e32 v1, 16, v192
	v_and_b32_e32 v141, 0xffff0000, v192
	v_lshlrev_b32_e32 v144, 16, v193
	v_and_b32_e32 v145, 0xffff0000, v193
	v_lshlrev_b32_e32 v148, 16, v194
	v_and_b32_e32 v146, 0xffff0000, v194
	v_lshlrev_b32_e32 v149, 16, v195
	v_and_b32_e32 v147, 0xffff0000, v195
	v_max_f32_e32 v1, v1, v1
	v_max_f32_e32 v141, v141, v141
	v_max_f32_e32 v144, v144, v144
	v_max_f32_e32 v145, v145, v145
	v_max_f32_e32 v148, v148, v148
	v_max_f32_e32 v146, v146, v146
	v_max_f32_e32 v149, v149, v149
	v_max_f32_e32 v147, v147, v147
	v_max_f32_e32 v1, 0xc1f00000, v1
	v_max_f32_e32 v141, 0xc1f00000, v141
	v_max_f32_e32 v144, 0xc1f00000, v144
	v_max_f32_e32 v145, 0xc1f00000, v145
	v_max_f32_e32 v148, 0xc1f00000, v148
	v_max_f32_e32 v146, 0xc1f00000, v146
	v_max_f32_e32 v149, 0xc1f00000, v149
	v_max_f32_e32 v147, 0xc1f00000, v147
	v_mul_f32_e32 v1, 0xbfb8aa3b, v1
	v_mul_f32_e32 v141, 0xbfb8aa3b, v141
	v_mul_f32_e32 v144, 0xbfb8aa3b, v144
	v_mul_f32_e32 v145, 0xbfb8aa3b, v145
	v_mul_f32_e32 v148, 0xbfb8aa3b, v148
	v_mul_f32_e32 v146, 0xbfb8aa3b, v146
	v_mul_f32_e32 v149, 0xbfb8aa3b, v149
	v_mul_f32_e32 v147, 0xbfb8aa3b, v147
	v_exp_f32_e32 v1, v1
	v_exp_f32_e32 v141, v141
	v_exp_f32_e32 v144, v144
	v_exp_f32_e32 v145, v145
	v_exp_f32_e32 v148, v148
	v_exp_f32_e32 v146, v146
	v_exp_f32_e32 v149, v149
	v_exp_f32_e32 v147, v147
	v_add_f32_e32 v1, 1.0, v1
	v_add_f32_e32 v141, 1.0, v141
	v_add_f32_e32 v150, 1.0, v144
	v_add_f32_e32 v151, 1.0, v145
	v_add_f32_e32 v148, 1.0, v148
	v_add_f32_e32 v174, 1.0, v146
	v_add_f32_e32 v149, 1.0, v149
	v_add_f32_e32 v175, 1.0, v147
	v_rcp_f32_e32 v144, v1
	v_rcp_f32_e32 v145, v141
	v_rcp_f32_e32 v146, v150
	v_rcp_f32_e32 v147, v151
	v_rcp_f32_e32 v148, v148
	v_rcp_f32_e32 v150, v149
	v_rcp_f32_e32 v151, v175
	v_rcp_f32_e32 v149, v174
	v_pk_mul_f32 v[146:147], v[122:123], v[146:147]
	v_pk_mul_f32 v[144:145], v[120:121], v[144:145]
	v_pk_mul_f32 v[150:151], v[118:119], v[150:151]
	v_pk_mul_f32 v[148:149], v[116:117], v[148:149]
	v_cvt_pk_bf16_f32 v144, v144, v145
	v_cvt_pk_bf16_f32 v145, v146, v147
	s_nop 0
	v_cvt_pk_bf16_f32 v146, v148, v149
	v_cvt_pk_bf16_f32 v147, v150, v151
	global_store_dwordx4 v[134:135], v[144:147], off
	v_lshl_add_u64 v[150:151], s[16:17], 0, v[136:137]
	v_lshlrev_b64 v[134:135], 10, v[170:171]
	v_lshl_add_u64 v[134:135], v[134:135], 0, v[168:169]
	v_lshlrev_b64 v[134:135], 1, v[134:135]
	v_lshl_add_u64 v[148:149], s[6:7], 0, v[134:135]
	s_waitcnt vmcnt(0)
; __device__ __forceinline__ float bf_lo(unsigned w) { return __uint_as_float(w << 16); }
; __device__ __forceinline__ float bf_hi(unsigned w) { return __uint_as_float(w & 0xffff0000u); }
; __device__ __forceinline__ float sigm(float x) { return __builtin_amdgcn_rcpf(1.0f + __builtin_amdgcn_exp2f(-1.4426950408889634f * x)); }
; __device__ __forceinline__ u32x4 pack8(f32x4 a, f32x4 b) { u32x4 w; w.x = cvt_pk_bf16(a[0], a[1]); w.y = cvt_pk_bf16(a[2], a[3]); w.z = cvt_pk_bf16(b[0], b[1]); w.w = cvt_pk_bf16(b[2], b[3]); return w; }
;     __device__ __forceinline__ void operator()(const f32x4 (&acc)[2][2][4][2], const Unit& u, int wr, int wc, int fr, int fq) const {
;     ...
;                 for (int bj = 0; bj < 2; ++bj) { const size_t o = ro + bj * HALF; const u32x4 b = *(const u32x4*)(GBr + o);
;                     f32x4 s0, s1; s0[0] = sigm(fmaxf(bf_lo(b.x), -30.f)); s0[1] = sigm(fmaxf(bf_hi(b.x), -30.f)); s0[2] = sigm(fmaxf(bf_lo(b.y), -30.f)); s0[3] = sigm(fmaxf(bf_hi(b.y), -30.f));
;                     s1[0] = sigm(fmaxf(bf_lo(b.z), -30.f)); s1[1] = sigm(fmaxf(bf_hi(b.z), -30.f)); s1[2] = sigm(fmaxf(bf_lo(b.w), -30.f)); s1[3] = sigm(fmaxf(bf_hi(b.w), -30.f));
;                     *(u32x4*)(Mx + o) = pack8(s0 * acc[ai][bj][m][0], s1 * acc[ai][bj][m][1]); } }
	v_lshlrev_b32_e32 v1, 16, v196
	v_and_b32_e32 v136, 0xffff0000, v196
	v_lshlrev_b32_e32 v137, 16, v197
	v_and_b32_e32 v138, 0xffff0000, v197
	v_lshlrev_b32_e32 v139, 16, v198
	v_and_b32_e32 v141, 0xffff0000, v198
	v_lshlrev_b32_e32 v144, 16, v199
	v_and_b32_e32 v145, 0xffff0000, v199
	v_max_f32_e32 v1, v1, v1
	v_max_f32_e32 v136, v136, v136
	v_max_f32_e32 v137, v137, v137
	v_max_f32_e32 v138, v138, v138
	v_max_f32_e32 v139, v139, v139
	v_max_f32_e32 v141, v141, v141
	v_max_f32_e32 v144, v144, v144
	v_max_f32_e32 v145, v145, v145
	v_max_f32_e32 v1, 0xc1f00000, v1
	v_max_f32_e32 v136, 0xc1f00000, v136
	v_max_f32_e32 v137, 0xc1f00000, v137
	v_max_f32_e32 v138, 0xc1f00000, v138
	v_max_f32_e32 v139, 0xc1f00000, v139
	v_max_f32_e32 v141, 0xc1f00000, v141
	v_max_f32_e32 v144, 0xc1f00000, v144
	v_max_f32_e32 v145, 0xc1f00000, v145
	v_mul_f32_e32 v1, 0xbfb8aa3b, v1
	v_mul_f32_e32 v136, 0xbfb8aa3b, v136
	v_mul_f32_e32 v137, 0xbfb8aa3b, v137
	v_mul_f32_e32 v138, 0xbfb8aa3b, v138
	v_mul_f32_e32 v139, 0xbfb8aa3b, v139
	v_mul_f32_e32 v141, 0xbfb8aa3b, v141
	v_mul_f32_e32 v144, 0xbfb8aa3b, v144
	v_mul_f32_e32 v145, 0xbfb8aa3b, v145
	v_exp_f32_e32 v1, v1
	v_exp_f32_e32 v136, v136
	v_exp_f32_e32 v137, v137
	v_exp_f32_e32 v138, v138
	v_exp_f32_e32 v139, v139
	v_exp_f32_e32 v141, v141
	v_exp_f32_e32 v144, v144
	v_exp_f32_e32 v145, v145
	v_add_f32_e32 v1, 1.0, v1
	v_add_f32_e32 v146, 1.0, v136
	v_add_f32_e32 v147, 1.0, v137
	v_add_f32_e32 v174, 1.0, v138
	v_add_f32_e32 v175, 1.0, v139
	v_add_f32_e32 v141, 1.0, v141
	v_add_f32_e32 v176, 1.0, v144
	v_add_f32_e32 v145, 1.0, v145
	v_rcp_f32_e32 v136, v1
	v_rcp_f32_e32 v137, v146
	v_rcp_f32_e32 v138, v147
	v_rcp_f32_e32 v139, v174
	v_rcp_f32_e32 v144, v175
	v_rcp_f32_e32 v146, v176
	v_rcp_f32_e32 v147, v145
	v_rcp_f32_e32 v145, v141
	v_pk_mul_f32 v[138:139], v[90:91], v[138:139]
	v_pk_mul_f32 v[136:137], v[88:89], v[136:137]
	v_pk_mul_f32 v[146:147], v[86:87], v[146:147]
	v_pk_mul_f32 v[144:145], v[84:85], v[144:145]
	v_cvt_pk_bf16_f32 v136, v136, v137
	v_cvt_pk_bf16_f32 v137, v138, v139
	s_nop 0
	v_cvt_pk_bf16_f32 v138, v144, v145
	v_cvt_pk_bf16_f32 v139, v146, v147
	global_store_dwordx4 v[150:151], v[136:139], off
	v_lshl_add_u64 v[144:145], s[16:17], 0, v[134:135]
	v_or_b32_e32 v134, 0x100, v134
	v_lshl_add_u64 v[146:147], s[6:7], 0, v[134:135]
	s_waitcnt vmcnt(0)
	v_lshlrev_b32_e32 v1, 16, v200
	v_and_b32_e32 v136, 0xffff0000, v200
	v_lshlrev_b32_e32 v141, 16, v201
	v_and_b32_e32 v137, 0xffff0000, v201
	v_lshlrev_b32_e32 v148, 16, v202
	v_and_b32_e32 v138, 0xffff0000, v202
	v_lshlrev_b32_e32 v149, 16, v203
	v_and_b32_e32 v139, 0xffff0000, v203
	v_max_f32_e32 v1, v1, v1
	v_max_f32_e32 v136, v136, v136
	v_max_f32_e32 v141, v141, v141
	v_max_f32_e32 v137, v137, v137
	v_max_f32_e32 v148, v148, v148
	v_max_f32_e32 v138, v138, v138
	v_max_f32_e32 v149, v149, v149
	v_max_f32_e32 v139, v139, v139
	v_max_f32_e32 v1, 0xc1f00000, v1
	v_max_f32_e32 v136, 0xc1f00000, v136
	v_max_f32_e32 v141, 0xc1f00000, v141
	v_max_f32_e32 v137, 0xc1f00000, v137
	v_max_f32_e32 v148, 0xc1f00000, v148
	v_max_f32_e32 v138, 0xc1f00000, v138
	v_max_f32_e32 v149, 0xc1f00000, v149
	v_max_f32_e32 v139, 0xc1f00000, v139
	v_mul_f32_e32 v1, 0xbfb8aa3b, v1
	v_mul_f32_e32 v136, 0xbfb8aa3b, v136
	v_mul_f32_e32 v141, 0xbfb8aa3b, v141
	v_mul_f32_e32 v137, 0xbfb8aa3b, v137
	v_mul_f32_e32 v148, 0xbfb8aa3b, v148
	v_mul_f32_e32 v138, 0xbfb8aa3b, v138
	v_mul_f32_e32 v149, 0xbfb8aa3b, v149
	v_mul_f32_e32 v139, 0xbfb8aa3b, v139
	v_exp_f32_e32 v1, v1
	v_exp_f32_e32 v136, v136
	v_exp_f32_e32 v141, v141
	v_exp_f32_e32 v137, v137
	v_exp_f32_e32 v148, v148
	v_exp_f32_e32 v138, v138
	v_exp_f32_e32 v149, v149
	v_exp_f32_e32 v139, v139
	v_add_f32_e32 v1, 1.0, v1
	v_add_f32_e32 v150, 1.0, v136
	v_add_f32_e32 v141, 1.0, v141
	v_add_f32_e32 v151, 1.0, v137
	v_add_f32_e32 v148, 1.0, v148
	v_add_f32_e32 v174, 1.0, v138
	v_add_f32_e32 v149, 1.0, v149
	v_add_f32_e32 v175, 1.0, v139
	v_rcp_f32_e32 v136, v1
	v_rcp_f32_e32 v137, v150
	v_rcp_f32_e32 v138, v141
	v_rcp_f32_e32 v139, v151
	v_rcp_f32_e32 v148, v148
	v_rcp_f32_e32 v150, v149
	v_rcp_f32_e32 v151, v175
	v_rcp_f32_e32 v149, v174
	v_pk_mul_f32 v[138:139], v[114:115], v[138:139]
	v_pk_mul_f32 v[136:137], v[112:113], v[136:137]
	v_pk_mul_f32 v[150:151], v[110:111], v[150:151]
	v_pk_mul_f32 v[148:149], v[108:109], v[148:149]
	v_cvt_pk_bf16_f32 v136, v136, v137
	v_cvt_pk_bf16_f32 v137, v138, v139
	s_nop 0
	v_cvt_pk_bf16_f32 v138, v148, v149
	v_cvt_pk_bf16_f32 v139, v150, v151
	global_store_dwordx4 v[144:145], v[136:139], off
	v_or_b32_e32 v144, 48, v2
	v_ashrrev_i32_e32 v145, 31, v144
	v_lshlrev_b64 v[144:145], 10, v[144:145]
	v_lshl_add_u64 v[144:145], v[144:145], 0, v[168:169]
	v_lshl_add_u64 v[146:147], s[16:17], 0, v[134:135]
	v_lshlrev_b64 v[134:135], 1, v[144:145]
	v_lshl_add_u64 v[144:145], s[6:7], 0, v[134:135]
	s_waitcnt vmcnt(0)
; __device__ __forceinline__ float bf_lo(unsigned w) { return __uint_as_float(w << 16); }
; __device__ __forceinline__ float bf_hi(unsigned w) { return __uint_as_float(w & 0xffff0000u); }
; __device__ __forceinline__ float sigm(float x) { return __builtin_amdgcn_rcpf(1.0f + __builtin_amdgcn_exp2f(-1.4426950408889634f * x)); }
; __device__ __forceinline__ u32x4 pack8(f32x4 a, f32x4 b) { u32x4 w; w.x = cvt_pk_bf16(a[0], a[1]); w.y = cvt_pk_bf16(a[2], a[3]); w.z = cvt_pk_bf16(b[0], b[1]); w.w = cvt_pk_bf16(b[2], b[3]); return w; }
;     __device__ __forceinline__ void operator()(const f32x4 (&acc)[2][2][4][2], const Unit& u, int wr, int wc, int fr, int fq) const {
;     ...
;                 for (int bj = 0; bj < 2; ++bj) { const size_t o = ro + bj * HALF; const u32x4 b = *(const u32x4*)(GBr + o);
;                     f32x4 s0, s1; s0[0] = sigm(fmaxf(bf_lo(b.x), -30.f)); s0[1] = sigm(fmaxf(bf_hi(b.x), -30.f)); s0[2] = sigm(fmaxf(bf_lo(b.y), -30.f)); s0[3] = sigm(fmaxf(bf_hi(b.y), -30.f));
;                     s1[0] = sigm(fmaxf(bf_lo(b.z), -30.f)); s1[1] = sigm(fmaxf(bf_hi(b.z), -30.f)); s1[2] = sigm(fmaxf(bf_lo(b.w), -30.f)); s1[3] = sigm(fmaxf(bf_hi(b.w), -30.f));
;                     *(u32x4*)(Mx + o) = pack8(s0 * acc[ai][bj][m][0], s1 * acc[ai][bj][m][1]); } }
	v_lshlrev_b32_e32 v1, 16, v204
	v_and_b32_e32 v136, 0xffff0000, v204
	v_lshlrev_b32_e32 v141, 16, v205
	v_and_b32_e32 v137, 0xffff0000, v205
	v_lshlrev_b32_e32 v148, 16, v206
	v_and_b32_e32 v138, 0xffff0000, v206
	v_lshlrev_b32_e32 v149, 16, v207
	v_and_b32_e32 v139, 0xffff0000, v207
	v_max_f32_e32 v1, v1, v1
	v_max_f32_e32 v136, v136, v136
	v_max_f32_e32 v141, v141, v141
	v_max_f32_e32 v137, v137, v137
	v_max_f32_e32 v148, v148, v148
	v_max_f32_e32 v138, v138, v138
	v_max_f32_e32 v149, v149, v149
	v_max_f32_e32 v139, v139, v139
	v_max_f32_e32 v1, 0xc1f00000, v1
	v_max_f32_e32 v136, 0xc1f00000, v136
	v_max_f32_e32 v141, 0xc1f00000, v141
	v_max_f32_e32 v137, 0xc1f00000, v137
	v_max_f32_e32 v148, 0xc1f00000, v148
	v_max_f32_e32 v138, 0xc1f00000, v138
	v_max_f32_e32 v149, 0xc1f00000, v149
	v_max_f32_e32 v139, 0xc1f00000, v139
	v_mul_f32_e32 v1, 0xbfb8aa3b, v1
	v_mul_f32_e32 v136, 0xbfb8aa3b, v136
	v_mul_f32_e32 v141, 0xbfb8aa3b, v141
	v_mul_f32_e32 v137, 0xbfb8aa3b, v137
	v_mul_f32_e32 v148, 0xbfb8aa3b, v148
	v_mul_f32_e32 v138, 0xbfb8aa3b, v138
	v_mul_f32_e32 v149, 0xbfb8aa3b, v149
	v_mul_f32_e32 v139, 0xbfb8aa3b, v139
	v_exp_f32_e32 v1, v1
	v_exp_f32_e32 v136, v136
	v_exp_f32_e32 v141, v141
	v_exp_f32_e32 v137, v137
	v_exp_f32_e32 v148, v148
	v_exp_f32_e32 v138, v138
	v_exp_f32_e32 v149, v149
	v_exp_f32_e32 v139, v139
	v_add_f32_e32 v1, 1.0, v1
	v_add_f32_e32 v150, 1.0, v136
	v_add_f32_e32 v141, 1.0, v141
	v_add_f32_e32 v151, 1.0, v137
	v_add_f32_e32 v148, 1.0, v148
	v_add_f32_e32 v174, 1.0, v138
	v_add_f32_e32 v149, 1.0, v149
	v_add_f32_e32 v175, 1.0, v139
	v_rcp_f32_e32 v136, v1
	v_rcp_f32_e32 v137, v150
	v_rcp_f32_e32 v138, v141
	v_rcp_f32_e32 v139, v151
	v_rcp_f32_e32 v148, v148
	v_rcp_f32_e32 v150, v149
	v_rcp_f32_e32 v151, v175
	v_rcp_f32_e32 v149, v174
	v_pk_mul_f32 v[138:139], v[82:83], v[138:139]
	v_pk_mul_f32 v[136:137], v[80:81], v[136:137]
	v_pk_mul_f32 v[150:151], v[78:79], v[150:151]
	v_pk_mul_f32 v[148:149], v[76:77], v[148:149]
	v_cvt_pk_bf16_f32 v136, v136, v137
	v_cvt_pk_bf16_f32 v137, v138, v139
	s_nop 0
	v_cvt_pk_bf16_f32 v138, v148, v149
	v_cvt_pk_bf16_f32 v139, v150, v151
	global_store_dwordx4 v[146:147], v[136:139], off
	v_lshl_add_u64 v[144:145], s[16:17], 0, v[134:135]
	v_or_b32_e32 v134, 0x100, v134
	v_lshl_add_u64 v[146:147], s[6:7], 0, v[134:135]
	s_waitcnt vmcnt(0)
	v_lshlrev_b32_e32 v1, 16, v208
	v_and_b32_e32 v136, 0xffff0000, v208
	v_lshlrev_b32_e32 v141, 16, v209
	v_and_b32_e32 v137, 0xffff0000, v209
	v_lshlrev_b32_e32 v148, 16, v210
	v_and_b32_e32 v138, 0xffff0000, v210
	v_lshlrev_b32_e32 v149, 16, v211
	v_and_b32_e32 v139, 0xffff0000, v211
	v_max_f32_e32 v1, v1, v1
	v_max_f32_e32 v136, v136, v136
	v_max_f32_e32 v141, v141, v141
	v_max_f32_e32 v137, v137, v137
	v_max_f32_e32 v148, v148, v148
	v_max_f32_e32 v138, v138, v138
	v_max_f32_e32 v149, v149, v149
	v_max_f32_e32 v139, v139, v139
	v_max_f32_e32 v1, 0xc1f00000, v1
	v_max_f32_e32 v136, 0xc1f00000, v136
	v_max_f32_e32 v141, 0xc1f00000, v141
	v_max_f32_e32 v137, 0xc1f00000, v137
	v_max_f32_e32 v148, 0xc1f00000, v148
	v_max_f32_e32 v138, 0xc1f00000, v138
	v_max_f32_e32 v149, 0xc1f00000, v149
	v_max_f32_e32 v139, 0xc1f00000, v139
	v_mul_f32_e32 v1, 0xbfb8aa3b, v1
	v_mul_f32_e32 v136, 0xbfb8aa3b, v136
	v_mul_f32_e32 v141, 0xbfb8aa3b, v141
	v_mul_f32_e32 v137, 0xbfb8aa3b, v137
	v_mul_f32_e32 v148, 0xbfb8aa3b, v148
	v_mul_f32_e32 v138, 0xbfb8aa3b, v138
	v_mul_f32_e32 v149, 0xbfb8aa3b, v149
	v_mul_f32_e32 v139, 0xbfb8aa3b, v139
	v_exp_f32_e32 v1, v1
	v_exp_f32_e32 v136, v136
	v_exp_f32_e32 v141, v141
	v_exp_f32_e32 v137, v137
	v_exp_f32_e32 v148, v148
	v_exp_f32_e32 v138, v138
	v_exp_f32_e32 v149, v149
	v_exp_f32_e32 v139, v139
	v_add_f32_e32 v1, 1.0, v1
	v_add_f32_e32 v150, 1.0, v136
	v_add_f32_e32 v141, 1.0, v141
	v_add_f32_e32 v151, 1.0, v137
	v_add_f32_e32 v148, 1.0, v148
	v_add_f32_e32 v174, 1.0, v138
	v_add_f32_e32 v149, 1.0, v149
	v_add_f32_e32 v175, 1.0, v139
	v_rcp_f32_e32 v136, v1
	v_rcp_f32_e32 v137, v150
	v_rcp_f32_e32 v138, v141
	v_rcp_f32_e32 v139, v151
	v_rcp_f32_e32 v148, v148
	v_rcp_f32_e32 v150, v149
	v_rcp_f32_e32 v151, v175
	v_rcp_f32_e32 v149, v174
	v_pk_mul_f32 v[138:139], v[106:107], v[138:139]
	v_pk_mul_f32 v[136:137], v[104:105], v[136:137]
	v_pk_mul_f32 v[150:151], v[102:103], v[150:151]
	v_pk_mul_f32 v[148:149], v[100:101], v[148:149]
	v_cvt_pk_bf16_f32 v136, v136, v137
	v_cvt_pk_bf16_f32 v137, v138, v139
	s_nop 0
	v_cvt_pk_bf16_f32 v138, v148, v149
	v_cvt_pk_bf16_f32 v139, v150, v151
	global_store_dwordx4 v[144:145], v[136:139], off
	v_lshl_add_u64 v[148:149], s[16:17], 0, v[134:135]
	v_lshl_add_u64 v[144:145], v[142:143], 0, s[18:19]
	v_lshl_add_u64 v[146:147], s[6:7], 0, v[144:145]
	v_lshl_add_u64 v[144:145], s[16:17], 0, v[144:145]
	s_waitcnt vmcnt(0)
; __device__ __forceinline__ float bf_lo(unsigned w) { return __uint_as_float(w << 16); }
; __device__ __forceinline__ float bf_hi(unsigned w) { return __uint_as_float(w & 0xffff0000u); }
; __device__ __forceinline__ float sigm(float x) { return __builtin_amdgcn_rcpf(1.0f + __builtin_amdgcn_exp2f(-1.4426950408889634f * x)); }
; __device__ __forceinline__ u32x4 pack8(f32x4 a, f32x4 b) { u32x4 w; w.x = cvt_pk_bf16(a[0], a[1]); w.y = cvt_pk_bf16(a[2], a[3]); w.z = cvt_pk_bf16(b[0], b[1]); w.w = cvt_pk_bf16(b[2], b[3]); return w; }
;     __device__ __forceinline__ void operator()(const f32x4 (&acc)[2][2][4][2], const Unit& u, int wr, int wc, int fr, int fq) const {
;     ...
;                 for (int bj = 0; bj < 2; ++bj) { const size_t o = ro + bj * HALF; const u32x4 b = *(const u32x4*)(GBr + o);
;                     f32x4 s0, s1; s0[0] = sigm(fmaxf(bf_lo(b.x), -30.f)); s0[1] = sigm(fmaxf(bf_hi(b.x), -30.f)); s0[2] = sigm(fmaxf(bf_lo(b.y), -30.f)); s0[3] = sigm(fmaxf(bf_hi(b.y), -30.f));
;                     s1[0] = sigm(fmaxf(bf_lo(b.z), -30.f)); s1[1] = sigm(fmaxf(bf_hi(b.z), -30.f)); s1[2] = sigm(fmaxf(bf_lo(b.w), -30.f)); s1[3] = sigm(fmaxf(bf_hi(b.w), -30.f));
;                     *(u32x4*)(Mx + o) = pack8(s0 * acc[ai][bj][m][0], s1 * acc[ai][bj][m][1]); } }
	v_lshlrev_b32_e32 v1, 16, v212
	v_and_b32_e32 v134, 0xffff0000, v212
	v_lshlrev_b32_e32 v135, 16, v213
	v_and_b32_e32 v136, 0xffff0000, v213
	v_lshlrev_b32_e32 v137, 16, v214
	v_and_b32_e32 v138, 0xffff0000, v214
	v_lshlrev_b32_e32 v141, 16, v215
	v_and_b32_e32 v139, 0xffff0000, v215
	v_max_f32_e32 v1, v1, v1
	v_max_f32_e32 v134, v134, v134
	v_max_f32_e32 v135, v135, v135
	v_max_f32_e32 v136, v136, v136
	v_max_f32_e32 v137, v137, v137
	v_max_f32_e32 v138, v138, v138
	v_max_f32_e32 v141, v141, v141
	v_max_f32_e32 v139, v139, v139
	v_max_f32_e32 v1, 0xc1f00000, v1
	v_max_f32_e32 v134, 0xc1f00000, v134
	v_max_f32_e32 v135, 0xc1f00000, v135
	v_max_f32_e32 v136, 0xc1f00000, v136
	v_max_f32_e32 v137, 0xc1f00000, v137
	v_max_f32_e32 v138, 0xc1f00000, v138
	v_max_f32_e32 v141, 0xc1f00000, v141
	v_max_f32_e32 v139, 0xc1f00000, v139
	v_mul_f32_e32 v1, 0xbfb8aa3b, v1
	v_mul_f32_e32 v134, 0xbfb8aa3b, v134
	v_mul_f32_e32 v135, 0xbfb8aa3b, v135
	v_mul_f32_e32 v136, 0xbfb8aa3b, v136
	v_mul_f32_e32 v137, 0xbfb8aa3b, v137
	v_mul_f32_e32 v138, 0xbfb8aa3b, v138
	v_mul_f32_e32 v141, 0xbfb8aa3b, v141
	v_mul_f32_e32 v139, 0xbfb8aa3b, v139
	v_exp_f32_e32 v1, v1
	v_exp_f32_e32 v134, v134
	v_exp_f32_e32 v135, v135
	v_exp_f32_e32 v136, v136
	v_exp_f32_e32 v137, v137
	v_exp_f32_e32 v138, v138
	v_exp_f32_e32 v141, v141
	v_exp_f32_e32 v139, v139
	v_add_f32_e32 v1, 1.0, v1
	v_add_f32_e32 v150, 1.0, v134
	v_add_f32_e32 v151, 1.0, v135
	v_add_f32_e32 v174, 1.0, v136
	v_add_f32_e32 v175, 1.0, v137
	v_add_f32_e32 v176, 1.0, v138
	v_add_f32_e32 v141, 1.0, v141
	v_add_f32_e32 v139, 1.0, v139
	v_rcp_f32_e32 v134, v1
	v_rcp_f32_e32 v135, v150
	v_rcp_f32_e32 v136, v151
	v_rcp_f32_e32 v137, v174
	v_rcp_f32_e32 v138, v175
	v_rcp_f32_e32 v150, v141
	v_rcp_f32_e32 v151, v139
	v_rcp_f32_e32 v139, v176
	v_pk_mul_f32 v[136:137], v[74:75], v[136:137]
	v_pk_mul_f32 v[134:135], v[72:73], v[134:135]
	v_pk_mul_f32 v[150:151], v[70:71], v[150:151]
	v_pk_mul_f32 v[138:139], v[68:69], v[138:139]
	v_cvt_pk_bf16_f32 v134, v134, v135
	v_cvt_pk_bf16_f32 v135, v136, v137
	s_nop 0
	v_cvt_pk_bf16_f32 v136, v138, v139
	v_cvt_pk_bf16_f32 v137, v150, v151
	global_store_dwordx4 v[148:149], v[134:137], off
	v_lshl_add_u64 v[138:139], v[142:143], 0, s[30:31]
	v_lshl_add_u64 v[146:147], s[6:7], 0, v[138:139]
	v_lshl_add_u64 v[138:139], s[16:17], 0, v[138:139]
	s_waitcnt vmcnt(0)
	v_lshlrev_b32_e32 v1, 16, v216
	v_and_b32_e32 v134, 0xffff0000, v216
	v_lshlrev_b32_e32 v141, 16, v217
	v_and_b32_e32 v135, 0xffff0000, v217
	v_lshlrev_b32_e32 v148, 16, v218
	v_and_b32_e32 v136, 0xffff0000, v218
	v_lshlrev_b32_e32 v149, 16, v219
	v_and_b32_e32 v137, 0xffff0000, v219
	v_max_f32_e32 v1, v1, v1
	v_max_f32_e32 v134, v134, v134
	v_max_f32_e32 v141, v141, v141
	v_max_f32_e32 v135, v135, v135
	v_max_f32_e32 v148, v148, v148
	v_max_f32_e32 v136, v136, v136
	v_max_f32_e32 v149, v149, v149
	v_max_f32_e32 v137, v137, v137
	v_max_f32_e32 v1, 0xc1f00000, v1
	v_max_f32_e32 v134, 0xc1f00000, v134
	v_max_f32_e32 v141, 0xc1f00000, v141
	v_max_f32_e32 v135, 0xc1f00000, v135
	v_max_f32_e32 v148, 0xc1f00000, v148
	v_max_f32_e32 v136, 0xc1f00000, v136
	v_max_f32_e32 v149, 0xc1f00000, v149
	v_max_f32_e32 v137, 0xc1f00000, v137
	v_mul_f32_e32 v1, 0xbfb8aa3b, v1
	v_mul_f32_e32 v134, 0xbfb8aa3b, v134
	v_mul_f32_e32 v141, 0xbfb8aa3b, v141
	v_mul_f32_e32 v135, 0xbfb8aa3b, v135
	v_mul_f32_e32 v148, 0xbfb8aa3b, v148
	v_mul_f32_e32 v136, 0xbfb8aa3b, v136
	v_mul_f32_e32 v149, 0xbfb8aa3b, v149
	v_mul_f32_e32 v137, 0xbfb8aa3b, v137
	v_exp_f32_e32 v1, v1
	v_exp_f32_e32 v134, v134
	v_exp_f32_e32 v141, v141
	v_exp_f32_e32 v135, v135
	v_exp_f32_e32 v148, v148
	v_exp_f32_e32 v136, v136
	v_exp_f32_e32 v149, v149
	v_exp_f32_e32 v137, v137
	v_add_f32_e32 v1, 1.0, v1
	v_add_f32_e32 v150, 1.0, v134
	v_add_f32_e32 v141, 1.0, v141
	v_add_f32_e32 v151, 1.0, v135
	v_add_f32_e32 v148, 1.0, v148
	v_add_f32_e32 v174, 1.0, v136
	v_add_f32_e32 v149, 1.0, v149
	v_add_f32_e32 v175, 1.0, v137
	v_rcp_f32_e32 v134, v1
	v_rcp_f32_e32 v135, v150
	v_rcp_f32_e32 v136, v141
	v_rcp_f32_e32 v137, v151
	v_rcp_f32_e32 v148, v148
	v_rcp_f32_e32 v150, v149
	v_rcp_f32_e32 v151, v175
	v_rcp_f32_e32 v149, v174
	v_pk_mul_f32 v[136:137], v[66:67], v[136:137]
	v_pk_mul_f32 v[134:135], v[64:65], v[134:135]
	v_pk_mul_f32 v[150:151], v[62:63], v[150:151]
	v_pk_mul_f32 v[148:149], v[60:61], v[148:149]
	v_cvt_pk_bf16_f32 v134, v134, v135
	v_cvt_pk_bf16_f32 v135, v136, v137
	s_nop 0
	v_cvt_pk_bf16_f32 v136, v148, v149
	v_cvt_pk_bf16_f32 v137, v150, v151
	global_store_dwordx4 v[144:145], v[134:137], off
	v_lshl_add_u64 v[144:145], v[142:143], 0, s[34:35]
	v_lshl_add_u64 v[146:147], s[6:7], 0, v[144:145]
	v_lshl_add_u64 v[144:145], s[16:17], 0, v[144:145]
	s_waitcnt vmcnt(0)
; __device__ __forceinline__ float bf_lo(unsigned w) { return __uint_as_float(w << 16); }
; __device__ __forceinline__ float bf_hi(unsigned w) { return __uint_as_float(w & 0xffff0000u); }
; __device__ __forceinline__ float sigm(float x) { return __builtin_amdgcn_rcpf(1.0f + __builtin_amdgcn_exp2f(-1.4426950408889634f * x)); }
; __device__ __forceinline__ u32x4 pack8(f32x4 a, f32x4 b) { u32x4 w; w.x = cvt_pk_bf16(a[0], a[1]); w.y = cvt_pk_bf16(a[2], a[3]); w.z = cvt_pk_bf16(b[0], b[1]); w.w = cvt_pk_bf16(b[2], b[3]); return w; }
;     __device__ __forceinline__ void operator()(const f32x4 (&acc)[2][2][4][2], const Unit& u, int wr, int wc, int fr, int fq) const {
;     ...
;                 for (int bj = 0; bj < 2; ++bj) { const size_t o = ro + bj * HALF; const u32x4 b = *(const u32x4*)(GBr + o);
;                     f32x4 s0, s1; s0[0] = sigm(fmaxf(bf_lo(b.x), -30.f)); s0[1] = sigm(fmaxf(bf_hi(b.x), -30.f)); s0[2] = sigm(fmaxf(bf_lo(b.y), -30.f)); s0[3] = sigm(fmaxf(bf_hi(b.y), -30.f));
;                     s1[0] = sigm(fmaxf(bf_lo(b.z), -30.f)); s1[1] = sigm(fmaxf(bf_hi(b.z), -30.f)); s1[2] = sigm(fmaxf(bf_lo(b.w), -30.f)); s1[3] = sigm(fmaxf(bf_hi(b.w), -30.f));
;                     *(u32x4*)(Mx + o) = pack8(s0 * acc[ai][bj][m][0], s1 * acc[ai][bj][m][1]); } }
	v_lshlrev_b32_e32 v1, 16, v220
	v_and_b32_e32 v134, 0xffff0000, v220
	v_lshlrev_b32_e32 v141, 16, v221
	v_and_b32_e32 v135, 0xffff0000, v221
	v_lshlrev_b32_e32 v148, 16, v222
	v_and_b32_e32 v136, 0xffff0000, v222
	v_lshlrev_b32_e32 v149, 16, v223
	v_and_b32_e32 v137, 0xffff0000, v223
	v_max_f32_e32 v1, v1, v1
	v_max_f32_e32 v134, v134, v134
	v_max_f32_e32 v141, v141, v141
	v_max_f32_e32 v135, v135, v135
	v_max_f32_e32 v148, v148, v148
	v_max_f32_e32 v136, v136, v136
	v_max_f32_e32 v149, v149, v149
	v_max_f32_e32 v137, v137, v137
	v_max_f32_e32 v1, 0xc1f00000, v1
	v_max_f32_e32 v134, 0xc1f00000, v134
	v_max_f32_e32 v141, 0xc1f00000, v141
	v_max_f32_e32 v135, 0xc1f00000, v135
	v_max_f32_e32 v148, 0xc1f00000, v148
	v_max_f32_e32 v136, 0xc1f00000, v136
	v_max_f32_e32 v149, 0xc1f00000, v149
	v_max_f32_e32 v137, 0xc1f00000, v137
	v_mul_f32_e32 v1, 0xbfb8aa3b, v1
	v_mul_f32_e32 v134, 0xbfb8aa3b, v134
	v_mul_f32_e32 v141, 0xbfb8aa3b, v141
	v_mul_f32_e32 v135, 0xbfb8aa3b, v135
	v_mul_f32_e32 v148, 0xbfb8aa3b, v148
	v_mul_f32_e32 v136, 0xbfb8aa3b, v136
	v_mul_f32_e32 v149, 0xbfb8aa3b, v149
	v_mul_f32_e32 v137, 0xbfb8aa3b, v137
	v_exp_f32_e32 v1, v1
	v_exp_f32_e32 v134, v134
	v_exp_f32_e32 v141, v141
	v_exp_f32_e32 v135, v135
	v_exp_f32_e32 v148, v148
	v_exp_f32_e32 v136, v136
	v_exp_f32_e32 v149, v149
	v_exp_f32_e32 v137, v137
	v_add_f32_e32 v1, 1.0, v1
	v_add_f32_e32 v150, 1.0, v134
	v_add_f32_e32 v141, 1.0, v141
	v_add_f32_e32 v151, 1.0, v135
	v_add_f32_e32 v148, 1.0, v148
	v_add_f32_e32 v174, 1.0, v136
	v_add_f32_e32 v149, 1.0, v149
	v_add_f32_e32 v175, 1.0, v137
	v_rcp_f32_e32 v134, v1
	v_rcp_f32_e32 v135, v150
	v_rcp_f32_e32 v136, v141
	v_rcp_f32_e32 v137, v151
	v_rcp_f32_e32 v148, v148
	v_rcp_f32_e32 v150, v149
	v_rcp_f32_e32 v151, v175
	v_rcp_f32_e32 v149, v174
	v_pk_mul_f32 v[136:137], v[34:35], v[136:137]
	v_pk_mul_f32 v[134:135], v[32:33], v[134:135]
	v_pk_mul_f32 v[150:151], v[30:31], v[150:151]
	v_pk_mul_f32 v[148:149], v[28:29], v[148:149]
	v_cvt_pk_bf16_f32 v134, v134, v135
	v_cvt_pk_bf16_f32 v135, v136, v137
	s_nop 0
	v_cvt_pk_bf16_f32 v136, v148, v149
	v_cvt_pk_bf16_f32 v137, v150, v151
	global_store_dwordx4 v[138:139], v[134:137], off
	v_lshl_add_u64 v[138:139], v[142:143], 0, s[36:37]
	v_lshl_add_u64 v[146:147], s[6:7], 0, v[138:139]
	v_lshl_add_u64 v[138:139], s[16:17], 0, v[138:139]
	s_waitcnt vmcnt(0)
	v_lshlrev_b32_e32 v1, 16, v224
	v_and_b32_e32 v134, 0xffff0000, v224
	v_lshlrev_b32_e32 v141, 16, v225
	v_and_b32_e32 v135, 0xffff0000, v225
	v_lshlrev_b32_e32 v148, 16, v226
	v_and_b32_e32 v136, 0xffff0000, v226
	v_lshlrev_b32_e32 v149, 16, v227
	v_and_b32_e32 v137, 0xffff0000, v227
	v_max_f32_e32 v1, v1, v1
	v_max_f32_e32 v134, v134, v134
	v_max_f32_e32 v141, v141, v141
	v_max_f32_e32 v135, v135, v135
	v_max_f32_e32 v148, v148, v148
	v_max_f32_e32 v136, v136, v136
	v_max_f32_e32 v149, v149, v149
	v_max_f32_e32 v137, v137, v137
	v_max_f32_e32 v1, 0xc1f00000, v1
	v_max_f32_e32 v134, 0xc1f00000, v134
	v_max_f32_e32 v141, 0xc1f00000, v141
	v_max_f32_e32 v135, 0xc1f00000, v135
	v_max_f32_e32 v148, 0xc1f00000, v148
	v_max_f32_e32 v136, 0xc1f00000, v136
	v_max_f32_e32 v149, 0xc1f00000, v149
	v_max_f32_e32 v137, 0xc1f00000, v137
	v_mul_f32_e32 v1, 0xbfb8aa3b, v1
	v_mul_f32_e32 v134, 0xbfb8aa3b, v134
	v_mul_f32_e32 v141, 0xbfb8aa3b, v141
	v_mul_f32_e32 v135, 0xbfb8aa3b, v135
	v_mul_f32_e32 v148, 0xbfb8aa3b, v148
	v_mul_f32_e32 v136, 0xbfb8aa3b, v136
	v_mul_f32_e32 v149, 0xbfb8aa3b, v149
	v_mul_f32_e32 v137, 0xbfb8aa3b, v137
	v_exp_f32_e32 v1, v1
	v_exp_f32_e32 v134, v134
	v_exp_f32_e32 v141, v141
	v_exp_f32_e32 v135, v135
	v_exp_f32_e32 v148, v148
	v_exp_f32_e32 v136, v136
	v_exp_f32_e32 v149, v149
	v_exp_f32_e32 v137, v137
	v_add_f32_e32 v1, 1.0, v1
	v_add_f32_e32 v150, 1.0, v134
	v_add_f32_e32 v141, 1.0, v141
	v_add_f32_e32 v151, 1.0, v135
	v_add_f32_e32 v148, 1.0, v148
	v_add_f32_e32 v174, 1.0, v136
	v_add_f32_e32 v149, 1.0, v149
	v_add_f32_e32 v175, 1.0, v137
	v_rcp_f32_e32 v134, v1
	v_rcp_f32_e32 v135, v150
	v_rcp_f32_e32 v136, v141
	v_rcp_f32_e32 v137, v151
	v_rcp_f32_e32 v148, v148
	v_rcp_f32_e32 v150, v149
	v_rcp_f32_e32 v151, v175
	v_rcp_f32_e32 v149, v174
	v_pk_mul_f32 v[136:137], v[58:59], v[136:137]
	v_pk_mul_f32 v[134:135], v[56:57], v[134:135]
	v_pk_mul_f32 v[150:151], v[54:55], v[150:151]
	v_pk_mul_f32 v[148:149], v[52:53], v[148:149]
	v_cvt_pk_bf16_f32 v134, v134, v135
	v_cvt_pk_bf16_f32 v135, v136, v137
	s_nop 0
	v_cvt_pk_bf16_f32 v136, v148, v149
	v_cvt_pk_bf16_f32 v137, v150, v151
	global_store_dwordx4 v[144:145], v[134:137], off
	v_lshl_add_u64 v[144:145], v[142:143], 0, s[38:39]
	v_lshl_add_u64 v[146:147], s[6:7], 0, v[144:145]
	v_lshl_add_u64 v[144:145], s[16:17], 0, v[144:145]
	s_waitcnt vmcnt(0)
; __device__ __forceinline__ float bf_lo(unsigned w) { return __uint_as_float(w << 16); }
; __device__ __forceinline__ float bf_hi(unsigned w) { return __uint_as_float(w & 0xffff0000u); }
; __device__ __forceinline__ float sigm(float x) { return __builtin_amdgcn_rcpf(1.0f + __builtin_amdgcn_exp2f(-1.4426950408889634f * x)); }
; __device__ __forceinline__ u32x4 pack8(f32x4 a, f32x4 b) { u32x4 w; w.x = cvt_pk_bf16(a[0], a[1]); w.y = cvt_pk_bf16(a[2], a[3]); w.z = cvt_pk_bf16(b[0], b[1]); w.w = cvt_pk_bf16(b[2], b[3]); return w; }
;     __device__ __forceinline__ void operator()(const f32x4 (&acc)[2][2][4][2], const Unit& u, int wr, int wc, int fr, int fq) const {
;     ...
;                 for (int bj = 0; bj < 2; ++bj) { const size_t o = ro + bj * HALF; const u32x4 b = *(const u32x4*)(GBr + o);
;                     f32x4 s0, s1; s0[0] = sigm(fmaxf(bf_lo(b.x), -30.f)); s0[1] = sigm(fmaxf(bf_hi(b.x), -30.f)); s0[2] = sigm(fmaxf(bf_lo(b.y), -30.f)); s0[3] = sigm(fmaxf(bf_hi(b.y), -30.f));
;                     s1[0] = sigm(fmaxf(bf_lo(b.z), -30.f)); s1[1] = sigm(fmaxf(bf_hi(b.z), -30.f)); s1[2] = sigm(fmaxf(bf_lo(b.w), -30.f)); s1[3] = sigm(fmaxf(bf_hi(b.w), -30.f));
;                     *(u32x4*)(Mx + o) = pack8(s0 * acc[ai][bj][m][0], s1 * acc[ai][bj][m][1]); } }
	v_lshlrev_b32_e32 v1, 16, v238
	v_and_b32_e32 v134, 0xffff0000, v238
	v_lshlrev_b32_e32 v141, 16, v239
	v_and_b32_e32 v135, 0xffff0000, v239
	v_lshlrev_b32_e32 v148, 16, v240
	v_and_b32_e32 v136, 0xffff0000, v240
	v_lshlrev_b32_e32 v149, 16, v241
	v_and_b32_e32 v137, 0xffff0000, v241
	v_max_f32_e32 v1, v1, v1
	v_max_f32_e32 v134, v134, v134
	v_max_f32_e32 v141, v141, v141
	v_max_f32_e32 v135, v135, v135
	v_max_f32_e32 v148, v148, v148
	v_max_f32_e32 v136, v136, v136
	v_max_f32_e32 v149, v149, v149
	v_max_f32_e32 v137, v137, v137
	v_max_f32_e32 v1, 0xc1f00000, v1
	v_max_f32_e32 v134, 0xc1f00000, v134
	v_max_f32_e32 v141, 0xc1f00000, v141
	v_max_f32_e32 v135, 0xc1f00000, v135
	v_max_f32_e32 v148, 0xc1f00000, v148
	v_max_f32_e32 v136, 0xc1f00000, v136
	v_max_f32_e32 v149, 0xc1f00000, v149
	v_max_f32_e32 v137, 0xc1f00000, v137
	v_mul_f32_e32 v1, 0xbfb8aa3b, v1
	v_mul_f32_e32 v134, 0xbfb8aa3b, v134
	v_mul_f32_e32 v141, 0xbfb8aa3b, v141
	v_mul_f32_e32 v135, 0xbfb8aa3b, v135
	v_mul_f32_e32 v148, 0xbfb8aa3b, v148
	v_mul_f32_e32 v136, 0xbfb8aa3b, v136
	v_mul_f32_e32 v149, 0xbfb8aa3b, v149
	v_mul_f32_e32 v137, 0xbfb8aa3b, v137
	v_exp_f32_e32 v1, v1
	v_exp_f32_e32 v134, v134
	v_exp_f32_e32 v141, v141
	v_exp_f32_e32 v135, v135
	v_exp_f32_e32 v148, v148
	v_exp_f32_e32 v136, v136
	v_exp_f32_e32 v149, v149
	v_exp_f32_e32 v137, v137
	v_add_f32_e32 v1, 1.0, v1
	v_add_f32_e32 v150, 1.0, v134
	v_add_f32_e32 v141, 1.0, v141
	v_add_f32_e32 v151, 1.0, v135
	v_add_f32_e32 v148, 1.0, v148
	v_add_f32_e32 v174, 1.0, v136
	v_add_f32_e32 v149, 1.0, v149
	v_add_f32_e32 v175, 1.0, v137
	v_rcp_f32_e32 v134, v1
	v_rcp_f32_e32 v135, v150
	v_rcp_f32_e32 v136, v141
	v_rcp_f32_e32 v137, v151
	v_rcp_f32_e32 v148, v148
	v_rcp_f32_e32 v150, v149
	v_rcp_f32_e32 v151, v175
	v_rcp_f32_e32 v149, v174
	v_pk_mul_f32 v[136:137], v[26:27], v[136:137]
	v_pk_mul_f32 v[134:135], v[24:25], v[134:135]
	v_pk_mul_f32 v[150:151], v[22:23], v[150:151]
	v_pk_mul_f32 v[148:149], v[20:21], v[148:149]
	v_cvt_pk_bf16_f32 v134, v134, v135
	v_cvt_pk_bf16_f32 v135, v136, v137
	s_nop 0
	v_cvt_pk_bf16_f32 v136, v148, v149
	v_cvt_pk_bf16_f32 v137, v150, v151
	global_store_dwordx4 v[138:139], v[134:137], off
	v_lshl_add_u64 v[138:139], v[142:143], 0, s[40:41]
	v_lshl_add_u64 v[146:147], s[6:7], 0, v[138:139]
	v_lshl_add_u64 v[138:139], s[16:17], 0, v[138:139]
	s_waitcnt vmcnt(0)
	v_lshlrev_b32_e32 v1, 16, v242
	v_and_b32_e32 v134, 0xffff0000, v242
	v_lshlrev_b32_e32 v141, 16, v243
	v_and_b32_e32 v135, 0xffff0000, v243
	v_lshlrev_b32_e32 v148, 16, v244
	v_and_b32_e32 v136, 0xffff0000, v244
	v_lshlrev_b32_e32 v149, 16, v245
	v_and_b32_e32 v137, 0xffff0000, v245
	v_max_f32_e32 v1, v1, v1
	v_max_f32_e32 v134, v134, v134
	v_max_f32_e32 v141, v141, v141
	v_max_f32_e32 v135, v135, v135
	v_max_f32_e32 v148, v148, v148
	v_max_f32_e32 v136, v136, v136
	v_max_f32_e32 v149, v149, v149
	v_max_f32_e32 v137, v137, v137
	v_max_f32_e32 v1, 0xc1f00000, v1
	v_max_f32_e32 v134, 0xc1f00000, v134
	v_max_f32_e32 v141, 0xc1f00000, v141
	v_max_f32_e32 v135, 0xc1f00000, v135
	v_max_f32_e32 v148, 0xc1f00000, v148
	v_max_f32_e32 v136, 0xc1f00000, v136
	v_max_f32_e32 v149, 0xc1f00000, v149
	v_max_f32_e32 v137, 0xc1f00000, v137
	v_mul_f32_e32 v1, 0xbfb8aa3b, v1
	v_mul_f32_e32 v134, 0xbfb8aa3b, v134
	v_mul_f32_e32 v141, 0xbfb8aa3b, v141
	v_mul_f32_e32 v135, 0xbfb8aa3b, v135
	v_mul_f32_e32 v148, 0xbfb8aa3b, v148
	v_mul_f32_e32 v136, 0xbfb8aa3b, v136
	v_mul_f32_e32 v149, 0xbfb8aa3b, v149
	v_mul_f32_e32 v137, 0xbfb8aa3b, v137
	v_exp_f32_e32 v1, v1
	v_exp_f32_e32 v134, v134
	v_exp_f32_e32 v141, v141
	v_exp_f32_e32 v135, v135
	v_exp_f32_e32 v148, v148
	v_exp_f32_e32 v136, v136
	v_exp_f32_e32 v149, v149
	v_exp_f32_e32 v137, v137
	v_add_f32_e32 v1, 1.0, v1
	v_add_f32_e32 v150, 1.0, v134
	v_add_f32_e32 v141, 1.0, v141
	v_add_f32_e32 v151, 1.0, v135
	v_add_f32_e32 v148, 1.0, v148
	v_add_f32_e32 v174, 1.0, v136
	v_add_f32_e32 v149, 1.0, v149
	v_add_f32_e32 v175, 1.0, v137
	v_rcp_f32_e32 v134, v1
	v_rcp_f32_e32 v135, v150
	v_rcp_f32_e32 v136, v141
	v_rcp_f32_e32 v137, v151
	v_rcp_f32_e32 v148, v148
	v_rcp_f32_e32 v150, v149
	v_rcp_f32_e32 v151, v175
	v_rcp_f32_e32 v149, v174
	v_pk_mul_f32 v[136:137], v[50:51], v[136:137]
	v_pk_mul_f32 v[134:135], v[48:49], v[134:135]
	v_pk_mul_f32 v[150:151], v[46:47], v[150:151]
	v_pk_mul_f32 v[148:149], v[44:45], v[148:149]
	v_cvt_pk_bf16_f32 v134, v134, v135
	v_cvt_pk_bf16_f32 v135, v136, v137
	s_nop 0
	v_cvt_pk_bf16_f32 v136, v148, v149
	v_cvt_pk_bf16_f32 v137, v150, v151
	global_store_dwordx4 v[144:145], v[134:137], off
	v_lshl_add_u64 v[144:145], v[142:143], 0, s[42:43]
	v_lshl_add_u64 v[146:147], s[6:7], 0, v[144:145]
	v_lshl_add_u64 v[144:145], s[16:17], 0, v[144:145]
	s_waitcnt vmcnt(0)
; __device__ __forceinline__ float bf_lo(unsigned w) { return __uint_as_float(w << 16); }
; __device__ __forceinline__ float bf_hi(unsigned w) { return __uint_as_float(w & 0xffff0000u); }
; __device__ __forceinline__ float sigm(float x) { return __builtin_amdgcn_rcpf(1.0f + __builtin_amdgcn_exp2f(-1.4426950408889634f * x)); }
; __device__ __forceinline__ u32x4 pack8(f32x4 a, f32x4 b) { u32x4 w; w.x = cvt_pk_bf16(a[0], a[1]); w.y = cvt_pk_bf16(a[2], a[3]); w.z = cvt_pk_bf16(b[0], b[1]); w.w = cvt_pk_bf16(b[2], b[3]); return w; }
;     __device__ __forceinline__ void operator()(const f32x4 (&acc)[2][2][4][2], const Unit& u, int wr, int wc, int fr, int fq) const {
;     ...
;                 for (int bj = 0; bj < 2; ++bj) { const size_t o = ro + bj * HALF; const u32x4 b = *(const u32x4*)(GBr + o);
;                     f32x4 s0, s1; s0[0] = sigm(fmaxf(bf_lo(b.x), -30.f)); s0[1] = sigm(fmaxf(bf_hi(b.x), -30.f)); s0[2] = sigm(fmaxf(bf_lo(b.y), -30.f)); s0[3] = sigm(fmaxf(bf_hi(b.y), -30.f));
;                     s1[0] = sigm(fmaxf(bf_lo(b.z), -30.f)); s1[1] = sigm(fmaxf(bf_hi(b.z), -30.f)); s1[2] = sigm(fmaxf(bf_lo(b.w), -30.f)); s1[3] = sigm(fmaxf(bf_hi(b.w), -30.f));
;                     *(u32x4*)(Mx + o) = pack8(s0 * acc[ai][bj][m][0], s1 * acc[ai][bj][m][1]); } }
	v_lshlrev_b32_e32 v1, 16, v246
	v_and_b32_e32 v134, 0xffff0000, v246
	v_lshlrev_b32_e32 v141, 16, v247
	v_and_b32_e32 v135, 0xffff0000, v247
	v_lshlrev_b32_e32 v148, 16, v248
	v_and_b32_e32 v136, 0xffff0000, v248
	v_lshlrev_b32_e32 v149, 16, v249
	v_and_b32_e32 v137, 0xffff0000, v249
	v_max_f32_e32 v1, v1, v1
	v_max_f32_e32 v134, v134, v134
	v_max_f32_e32 v141, v141, v141
	v_max_f32_e32 v135, v135, v135
	v_max_f32_e32 v148, v148, v148
	v_max_f32_e32 v136, v136, v136
	v_max_f32_e32 v149, v149, v149
	v_max_f32_e32 v137, v137, v137
	v_max_f32_e32 v1, 0xc1f00000, v1
	v_max_f32_e32 v134, 0xc1f00000, v134
	v_max_f32_e32 v141, 0xc1f00000, v141
	v_max_f32_e32 v135, 0xc1f00000, v135
	v_max_f32_e32 v148, 0xc1f00000, v148
	v_max_f32_e32 v136, 0xc1f00000, v136
	v_max_f32_e32 v149, 0xc1f00000, v149
	v_max_f32_e32 v137, 0xc1f00000, v137
	v_mul_f32_e32 v1, 0xbfb8aa3b, v1
	v_mul_f32_e32 v134, 0xbfb8aa3b, v134
	v_mul_f32_e32 v141, 0xbfb8aa3b, v141
	v_mul_f32_e32 v135, 0xbfb8aa3b, v135
	v_mul_f32_e32 v148, 0xbfb8aa3b, v148
	v_mul_f32_e32 v136, 0xbfb8aa3b, v136
	v_mul_f32_e32 v149, 0xbfb8aa3b, v149
	v_mul_f32_e32 v137, 0xbfb8aa3b, v137
	v_exp_f32_e32 v1, v1
	v_exp_f32_e32 v134, v134
	v_exp_f32_e32 v141, v141
	v_exp_f32_e32 v135, v135
	v_exp_f32_e32 v148, v148
	v_exp_f32_e32 v136, v136
	v_exp_f32_e32 v149, v149
	v_exp_f32_e32 v137, v137
	v_add_f32_e32 v1, 1.0, v1
	v_add_f32_e32 v150, 1.0, v134
	v_add_f32_e32 v141, 1.0, v141
	v_add_f32_e32 v151, 1.0, v135
	v_add_f32_e32 v148, 1.0, v148
	v_add_f32_e32 v174, 1.0, v136
	v_add_f32_e32 v149, 1.0, v149
	v_add_f32_e32 v175, 1.0, v137
	v_rcp_f32_e32 v134, v1
	v_rcp_f32_e32 v135, v150
	v_rcp_f32_e32 v136, v141
	v_rcp_f32_e32 v137, v151
	v_rcp_f32_e32 v148, v148
	v_rcp_f32_e32 v150, v149
	v_rcp_f32_e32 v151, v175
	v_rcp_f32_e32 v149, v174
	v_pk_mul_f32 v[136:137], v[18:19], v[136:137]
	v_pk_mul_f32 v[134:135], v[16:17], v[134:135]
	v_pk_mul_f32 v[150:151], v[14:15], v[150:151]
	v_pk_mul_f32 v[148:149], v[12:13], v[148:149]
	v_cvt_pk_bf16_f32 v134, v134, v135
	v_cvt_pk_bf16_f32 v135, v136, v137
	s_nop 0
	v_cvt_pk_bf16_f32 v136, v148, v149
	v_cvt_pk_bf16_f32 v137, v150, v151
	global_store_dwordx4 v[138:139], v[134:137], off
	v_lshl_add_u64 v[138:139], v[142:143], 0, s[44:45]
	v_lshl_add_u64 v[146:147], s[6:7], 0, v[138:139]
	v_lshl_add_u64 v[138:139], s[16:17], 0, v[138:139]
	s_waitcnt vmcnt(0)
	v_lshlrev_b32_e32 v1, 16, v252
	v_and_b32_e32 v134, 0xffff0000, v252
	v_lshlrev_b32_e32 v141, 16, v253
	v_and_b32_e32 v135, 0xffff0000, v253
	v_lshlrev_b32_e32 v148, 16, v254
	v_and_b32_e32 v136, 0xffff0000, v254
	v_lshlrev_b32_e32 v149, 16, v255
	v_and_b32_e32 v137, 0xffff0000, v255
	v_max_f32_e32 v1, v1, v1
	v_max_f32_e32 v134, v134, v134
	v_max_f32_e32 v141, v141, v141
	v_max_f32_e32 v135, v135, v135
	v_max_f32_e32 v148, v148, v148
	v_max_f32_e32 v136, v136, v136
	v_max_f32_e32 v149, v149, v149
	v_max_f32_e32 v137, v137, v137
	v_max_f32_e32 v1, 0xc1f00000, v1
	v_max_f32_e32 v134, 0xc1f00000, v134
	v_max_f32_e32 v141, 0xc1f00000, v141
	v_max_f32_e32 v135, 0xc1f00000, v135
	v_max_f32_e32 v148, 0xc1f00000, v148
	v_max_f32_e32 v136, 0xc1f00000, v136
	v_max_f32_e32 v149, 0xc1f00000, v149
	v_max_f32_e32 v137, 0xc1f00000, v137
	v_mul_f32_e32 v1, 0xbfb8aa3b, v1
	v_mul_f32_e32 v134, 0xbfb8aa3b, v134
	v_mul_f32_e32 v141, 0xbfb8aa3b, v141
	v_mul_f32_e32 v135, 0xbfb8aa3b, v135
	v_mul_f32_e32 v148, 0xbfb8aa3b, v148
	v_mul_f32_e32 v136, 0xbfb8aa3b, v136
	v_mul_f32_e32 v149, 0xbfb8aa3b, v149
	v_mul_f32_e32 v137, 0xbfb8aa3b, v137
	v_exp_f32_e32 v1, v1
	v_exp_f32_e32 v134, v134
	v_exp_f32_e32 v141, v141
	v_exp_f32_e32 v135, v135
	v_exp_f32_e32 v148, v148
	v_exp_f32_e32 v136, v136
	v_exp_f32_e32 v149, v149
	v_exp_f32_e32 v137, v137
	v_add_f32_e32 v1, 1.0, v1
	v_add_f32_e32 v150, 1.0, v134
	v_add_f32_e32 v141, 1.0, v141
	v_add_f32_e32 v151, 1.0, v135
	v_add_f32_e32 v148, 1.0, v148
	v_add_f32_e32 v174, 1.0, v136
	v_add_f32_e32 v149, 1.0, v149
	v_add_f32_e32 v175, 1.0, v137
	v_rcp_f32_e32 v134, v1
	v_rcp_f32_e32 v135, v150
	v_rcp_f32_e32 v136, v141
	v_rcp_f32_e32 v137, v151
	v_rcp_f32_e32 v148, v148
	v_rcp_f32_e32 v150, v149
	v_rcp_f32_e32 v151, v175
	v_rcp_f32_e32 v149, v174
	v_pk_mul_f32 v[136:137], v[42:43], v[136:137]
	v_pk_mul_f32 v[134:135], v[40:41], v[134:135]
	v_pk_mul_f32 v[150:151], v[38:39], v[150:151]
	v_pk_mul_f32 v[148:149], v[36:37], v[148:149]
	v_cvt_pk_bf16_f32 v134, v134, v135
	v_cvt_pk_bf16_f32 v135, v136, v137
	s_nop 0
	v_cvt_pk_bf16_f32 v136, v148, v149
	v_cvt_pk_bf16_f32 v137, v150, v151
	global_store_dwordx4 v[144:145], v[134:137], off
	s_waitcnt vmcnt(0)
	v_lshlrev_b32_e32 v1, 16, v184
	v_and_b32_e32 v134, 0xffff0000, v184
	v_lshlrev_b32_e32 v141, 16, v185
	v_and_b32_e32 v135, 0xffff0000, v185
	v_lshlrev_b32_e32 v144, 16, v186
	v_and_b32_e32 v136, 0xffff0000, v186
	v_lshlrev_b32_e32 v145, 16, v187
	v_and_b32_e32 v137, 0xffff0000, v187
	v_max_f32_e32 v1, v1, v1
	v_max_f32_e32 v134, v134, v134
	v_max_f32_e32 v141, v141, v141
	v_max_f32_e32 v135, v135, v135
	v_max_f32_e32 v144, v144, v144
	v_max_f32_e32 v136, v136, v136
	v_max_f32_e32 v145, v145, v145
	v_max_f32_e32 v137, v137, v137
	v_max_f32_e32 v1, 0xc1f00000, v1
	v_max_f32_e32 v134, 0xc1f00000, v134
	v_max_f32_e32 v141, 0xc1f00000, v141
	v_max_f32_e32 v135, 0xc1f00000, v135
	v_max_f32_e32 v144, 0xc1f00000, v144
	v_max_f32_e32 v136, 0xc1f00000, v136
	v_max_f32_e32 v145, 0xc1f00000, v145
	v_max_f32_e32 v137, 0xc1f00000, v137
	v_mul_f32_e32 v1, 0xbfb8aa3b, v1
	v_mul_f32_e32 v134, 0xbfb8aa3b, v134
	v_mul_f32_e32 v141, 0xbfb8aa3b, v141
	v_mul_f32_e32 v135, 0xbfb8aa3b, v135
	v_mul_f32_e32 v144, 0xbfb8aa3b, v144
	v_mul_f32_e32 v136, 0xbfb8aa3b, v136
	v_mul_f32_e32 v145, 0xbfb8aa3b, v145
	v_mul_f32_e32 v137, 0xbfb8aa3b, v137
	v_exp_f32_e32 v1, v1
	v_exp_f32_e32 v134, v134
	v_exp_f32_e32 v141, v141
	v_exp_f32_e32 v135, v135
	v_exp_f32_e32 v144, v144
	v_exp_f32_e32 v136, v136
	v_exp_f32_e32 v145, v145
	v_exp_f32_e32 v137, v137
	v_add_f32_e32 v1, 1.0, v1
	v_add_f32_e32 v146, 1.0, v134
	v_add_f32_e32 v141, 1.0, v141
	v_add_f32_e32 v147, 1.0, v135
	v_add_f32_e32 v144, 1.0, v144
	v_add_f32_e32 v148, 1.0, v136
	v_add_f32_e32 v145, 1.0, v145
	v_add_f32_e32 v149, 1.0, v137
	v_rcp_f32_e32 v134, v1
	v_rcp_f32_e32 v135, v146
	v_rcp_f32_e32 v136, v141
	v_rcp_f32_e32 v137, v147
	v_rcp_f32_e32 v144, v144
	v_rcp_f32_e32 v146, v145
	v_rcp_f32_e32 v147, v149
	v_rcp_f32_e32 v145, v148
	v_pk_mul_f32 v[136:137], v[10:11], v[136:137]
	v_pk_mul_f32 v[134:135], v[8:9], v[134:135]
	v_pk_mul_f32 v[146:147], v[6:7], v[146:147]
	v_pk_mul_f32 v[144:145], v[4:5], v[144:145]
	v_cvt_pk_bf16_f32 v134, v134, v135
	v_cvt_pk_bf16_f32 v135, v136, v137
	s_nop 0
	v_cvt_pk_bf16_f32 v136, v144, v145
	v_cvt_pk_bf16_f32 v137, v146, v147
	global_store_dwordx4 v[138:139], v[134:137], off
	s_cbranch_execnz .LBB0_1035

; __device__ __forceinline__ u32x4 pack8(f32x4 a, f32x4 b) { u32x4 w; w.x = cvt_pk_bf16(a[0], a[1]); w.y = cvt_pk_bf16(a[2], a[3]); w.z = cvt_pk_bf16(b[0], b[1]); w.w = cvt_pk_bf16(b[2], b[3]); return w; }
;     __device__ __forceinline__ void operator()(const f32x4 (&acc)[2][2][4][2], const Unit& u, int wr, int wc, int fr, int fq) const {
;         const int row0 = u.pm * BM + wr * 64 + fr, col0 = u.pn * BM + wc * 32 + 8 * fq;
;         const float* gp = gate + (size_t)(u.pm >> 5) * 6144 + col0;
;         f32x4 g[2][2];
; #pragma unroll
;         for (int bj = 0; bj < 2; ++bj) { g[bj][0] = *(const f32x4*)(gp + bj * HALF); g[bj][1] = *(const f32x4*)(gp + bj * HALF + 4); }
; #pragma unroll
;         for (int ai = 0; ai < 2; ++ai)
; #pragma unroll
;             for (int m = 0; m < 4; ++m) { const size_t ro = (size_t)(row0 + ai * HALF + m * 16) * 1024 + col0;
; #pragma unroll
;                 for (int bj = 0; bj < 2; ++bj) { const size_t o = ro + bj * HALF;
;                     if constexpr (!FINAL) { const f32x4 b0 = *(const f32x4*)(xin + o), b1 = *(const f32x4*)(xin + o + 4);
;                         *(u32x4*)(x1b + o) = pack8(b0 + g[bj][0] * acc[ai][bj][m][0], b1 + g[bj][1] * acc[ai][bj][m][1]); }
.LBB0_1134:
	v_lshl_add_u32 v164, s46, 8, v167
	v_lshl_or_b32 v162, s66, 8, v169
	s_ashr_i32 s39, s46, 5
	v_ashrrev_i32_e32 v165, 31, v164
	s_mul_hi_i32 s41, s39, 0x6000
	s_mulk_i32 s39, 0x6000
	v_ashrrev_i32_e32 v163, 31, v162
	v_lshlrev_b64 v[128:129], 10, v[164:165]
	s_add_u32 s48, s3, s39
	v_lshl_add_u64 v[160:161], v[128:129], 0, v[162:163]
	s_addc_u32 s49, s12, s41
	v_lshl_add_u64 v[182:183], v[160:161], 2, s[16:17]
	v_lshl_add_u64 v[132:133], v[162:163], 2, s[48:49]
	v_lshlrev_b64 v[184:185], 1, v[160:161]
	v_lshl_add_u64 v[186:187], s[6:7], 0, v[184:185]
	s_andn2_b64 vcc, exec, s[4:5]
	s_mov_b64 s[4:5], -1
	global_load_dwordx4 v[140:143], v[132:133], off
	global_load_dwordx4 v[136:139], v[132:133], off offset:16
	global_load_dwordx4 v[128:131], v[132:133], off offset:528
	s_nop 0
	global_load_dwordx4 v[132:135], v[132:133], off offset:512
	s_mov_b32 s98, 0x10000
	s_mov_b32 s99, 0
	s_mov_b32 s100, 0x8000
	s_mov_b32 s101, 0
	global_load_dwordx4 v[188:191], v[182:183], off
	global_load_dwordx4 v[192:195], v[182:183], off offset:16
	global_load_dwordx4 v[196:199], v[182:183], off offset:512
	global_load_dwordx4 v[200:203], v[182:183], off offset:528
	v_lshl_add_u64 v[182:183], v[182:183], 0, s[98:99]
	global_load_dwordx4 v[204:207], v[182:183], off
	global_load_dwordx4 v[208:211], v[182:183], off offset:16
	global_load_dwordx4 v[212:215], v[182:183], off offset:512
	global_load_dwordx4 v[216:219], v[182:183], off offset:528
	v_lshl_add_u64 v[182:183], v[182:183], 0, s[98:99]
	global_load_dwordx4 v[220:223], v[182:183], off
	global_load_dwordx4 v[224:227], v[182:183], off offset:16
	global_load_dwordx4 v[238:241], v[182:183], off offset:512
	global_load_dwordx4 v[242:245], v[182:183], off offset:528
	v_lshl_add_u64 v[182:183], v[182:183], 0, s[98:99]
	global_load_dwordx4 v[246:249], v[182:183], off
	global_load_dwordx4 v[252:255], v[182:183], off offset:16
	global_load_dwordx4 v[160:163], v[182:183], off offset:512
	global_load_dwordx4 v[174:177], v[182:183], off offset:528
	v_lshl_add_u64 v[182:183], v[182:183], 0, s[98:99]
	v_lshl_add_u64 v[182:183], v[182:183], 0, s[98:99]
	v_lshl_add_u64 v[182:183], v[182:183], 0, s[98:99]
	v_lshl_add_u64 v[182:183], v[182:183], 0, s[98:99]
	v_lshl_add_u64 v[182:183], v[182:183], 0, s[98:99]
	s_waitcnt vmcnt(14)
	v_pk_fma_f32 v[124:125], v[124:125], v[140:141], v[188:189]
	v_pk_fma_f32 v[126:127], v[126:127], v[142:143], v[190:191]
	v_pk_fma_f32 v[120:121], v[120:121], v[136:137], v[192:193]
	v_pk_fma_f32 v[122:123], v[122:123], v[138:139], v[194:195]
	global_load_dwordx4 v[188:191], v[182:183], off
	global_load_dwordx4 v[192:195], v[182:183], off offset:16
	v_cvt_pk_bf16_f32 v124, v124, v125
	v_cvt_pk_bf16_f32 v125, v126, v127
	v_cvt_pk_bf16_f32 v126, v120, v121
	v_cvt_pk_bf16_f32 v127, v122, v123
	global_store_dwordx4 v[186:187], v[124:127], off
	s_waitcnt vmcnt(14)
	v_pk_fma_f32 v[116:117], v[116:117], v[132:133], v[196:197]
	v_pk_fma_f32 v[118:119], v[118:119], v[134:135], v[198:199]
	v_pk_fma_f32 v[112:113], v[112:113], v[128:129], v[200:201]
	v_pk_fma_f32 v[114:115], v[114:115], v[130:131], v[202:203]
	global_load_dwordx4 v[196:199], v[182:183], off offset:512
	global_load_dwordx4 v[200:203], v[182:183], off offset:528
	v_lshl_add_u64 v[182:183], v[182:183], 0, s[98:99]
	v_cvt_pk_bf16_f32 v116, v116, v117
	v_cvt_pk_bf16_f32 v117, v118, v119
	v_cvt_pk_bf16_f32 v118, v112, v113
	v_cvt_pk_bf16_f32 v119, v114, v115
	global_store_dwordx4 v[186:187], v[116:119], off offset:256
	v_lshl_add_u64 v[186:187], v[186:187], 0, s[100:101]
	s_waitcnt vmcnt(14)
	v_pk_fma_f32 v[108:109], v[108:109], v[140:141], v[204:205]
	v_pk_fma_f32 v[110:111], v[110:111], v[142:143], v[206:207]
	v_pk_fma_f32 v[104:105], v[104:105], v[136:137], v[208:209]
	v_pk_fma_f32 v[106:107], v[106:107], v[138:139], v[210:211]
	global_load_dwordx4 v[204:207], v[182:183], off
	global_load_dwordx4 v[208:211], v[182:183], off offset:16
	v_cvt_pk_bf16_f32 v108, v108, v109
	v_cvt_pk_bf16_f32 v109, v110, v111
	v_cvt_pk_bf16_f32 v110, v104, v105
	v_cvt_pk_bf16_f32 v111, v106, v107
	global_store_dwordx4 v[186:187], v[108:111], off
	s_waitcnt vmcnt(14)
	v_pk_fma_f32 v[100:101], v[100:101], v[132:133], v[212:213]
	v_pk_fma_f32 v[102:103], v[102:103], v[134:135], v[214:215]
	v_pk_fma_f32 v[96:97], v[96:97], v[128:129], v[216:217]
	v_pk_fma_f32 v[98:99], v[98:99], v[130:131], v[218:219]
	global_load_dwordx4 v[212:215], v[182:183], off offset:512
	global_load_dwordx4 v[216:219], v[182:183], off offset:528
	v_lshl_add_u64 v[182:183], v[182:183], 0, s[98:99]
	v_cvt_pk_bf16_f32 v100, v100, v101
	v_cvt_pk_bf16_f32 v101, v102, v103
	v_cvt_pk_bf16_f32 v102, v96, v97
	v_cvt_pk_bf16_f32 v103, v98, v99
	global_store_dwordx4 v[186:187], v[100:103], off offset:256
	v_lshl_add_u64 v[186:187], v[186:187], 0, s[100:101]
	s_waitcnt vmcnt(14)
	v_pk_fma_f32 v[92:93], v[92:93], v[140:141], v[220:221]
	v_pk_fma_f32 v[94:95], v[94:95], v[142:143], v[222:223]
	v_pk_fma_f32 v[88:89], v[88:89], v[136:137], v[224:225]
	v_pk_fma_f32 v[90:91], v[90:91], v[138:139], v[226:227]
	global_load_dwordx4 v[220:223], v[182:183], off
	global_load_dwordx4 v[224:227], v[182:183], off offset:16
	v_cvt_pk_bf16_f32 v92, v92, v93
	v_cvt_pk_bf16_f32 v93, v94, v95
	v_cvt_pk_bf16_f32 v94, v88, v89
	v_cvt_pk_bf16_f32 v95, v90, v91
	global_store_dwordx4 v[186:187], v[92:95], off
	s_waitcnt vmcnt(14)
; __device__ __forceinline__ u32x4 pack8(f32x4 a, f32x4 b) { u32x4 w; w.x = cvt_pk_bf16(a[0], a[1]); w.y = cvt_pk_bf16(a[2], a[3]); w.z = cvt_pk_bf16(b[0], b[1]); w.w = cvt_pk_bf16(b[2], b[3]); return w; }
;     __device__ __forceinline__ void operator()(const f32x4 (&acc)[2][2][4][2], const Unit& u, int wr, int wc, int fr, int fq) const {
;     ...
;         for (int ai = 0; ai < 2; ++ai)
; #pragma unroll
;             for (int m = 0; m < 4; ++m) { const size_t ro = (size_t)(row0 + ai * HALF + m * 16) * 1024 + col0;
; #pragma unroll
;                 for (int bj = 0; bj < 2; ++bj) { const size_t o = ro + bj * HALF;
;                     if constexpr (!FINAL) { const f32x4 b0 = *(const f32x4*)(xin + o), b1 = *(const f32x4*)(xin + o + 4);
;                         *(u32x4*)(x1b + o) = pack8(b0 + g[bj][0] * acc[ai][bj][m][0], b1 + g[bj][1] * acc[ai][bj][m][1]); }
	v_pk_fma_f32 v[84:85], v[84:85], v[132:133], v[238:239]
	v_pk_fma_f32 v[86:87], v[86:87], v[134:135], v[240:241]
	v_pk_fma_f32 v[80:81], v[80:81], v[128:129], v[242:243]
	v_pk_fma_f32 v[82:83], v[82:83], v[130:131], v[244:245]
	global_load_dwordx4 v[238:241], v[182:183], off offset:512
	global_load_dwordx4 v[242:245], v[182:183], off offset:528
	v_lshl_add_u64 v[182:183], v[182:183], 0, s[98:99]
	v_cvt_pk_bf16_f32 v84, v84, v85
	v_cvt_pk_bf16_f32 v85, v86, v87
	v_cvt_pk_bf16_f32 v86, v80, v81
	v_cvt_pk_bf16_f32 v87, v82, v83
	global_store_dwordx4 v[186:187], v[84:87], off offset:256
	v_lshl_add_u64 v[186:187], v[186:187], 0, s[100:101]
	s_waitcnt vmcnt(14)
	v_pk_fma_f32 v[76:77], v[76:77], v[140:141], v[246:247]
	v_pk_fma_f32 v[78:79], v[78:79], v[142:143], v[248:249]
	v_pk_fma_f32 v[72:73], v[72:73], v[136:137], v[252:253]
	v_pk_fma_f32 v[74:75], v[74:75], v[138:139], v[254:255]
	global_load_dwordx4 v[246:249], v[182:183], off
	global_load_dwordx4 v[252:255], v[182:183], off offset:16
	v_cvt_pk_bf16_f32 v76, v76, v77
	v_cvt_pk_bf16_f32 v77, v78, v79
	v_cvt_pk_bf16_f32 v78, v72, v73
	v_cvt_pk_bf16_f32 v79, v74, v75
	global_store_dwordx4 v[186:187], v[76:79], off
	s_waitcnt vmcnt(14)
	v_pk_fma_f32 v[68:69], v[68:69], v[132:133], v[160:161]
	v_pk_fma_f32 v[70:71], v[70:71], v[134:135], v[162:163]
	v_pk_fma_f32 v[64:65], v[64:65], v[128:129], v[174:175]
	v_pk_fma_f32 v[66:67], v[66:67], v[130:131], v[176:177]
	global_load_dwordx4 v[160:163], v[182:183], off offset:512
	global_load_dwordx4 v[174:177], v[182:183], off offset:528
	v_cvt_pk_bf16_f32 v68, v68, v69
	v_cvt_pk_bf16_f32 v69, v70, v71
	v_cvt_pk_bf16_f32 v70, v64, v65
	v_cvt_pk_bf16_f32 v71, v66, v67
	global_store_dwordx4 v[186:187], v[68:71], off offset:256
	v_lshl_add_u64 v[186:187], v[186:187], 0, s[100:101]
	v_lshl_add_u64 v[186:187], v[186:187], 0, s[100:101]
	v_lshl_add_u64 v[186:187], v[186:187], 0, s[100:101]
	v_lshl_add_u64 v[186:187], v[186:187], 0, s[100:101]
	v_lshl_add_u64 v[186:187], v[186:187], 0, s[100:101]
	s_waitcnt vmcnt(14)
	v_pk_fma_f32 v[60:61], v[60:61], v[140:141], v[188:189]
	v_pk_fma_f32 v[62:63], v[62:63], v[142:143], v[190:191]
	v_pk_fma_f32 v[56:57], v[56:57], v[136:137], v[192:193]
	v_pk_fma_f32 v[58:59], v[58:59], v[138:139], v[194:195]
	v_cvt_pk_bf16_f32 v60, v60, v61
	v_cvt_pk_bf16_f32 v61, v62, v63
	v_cvt_pk_bf16_f32 v62, v56, v57
	v_cvt_pk_bf16_f32 v63, v58, v59
	global_store_dwordx4 v[186:187], v[60:63], off
	s_waitcnt vmcnt(12)
	v_pk_fma_f32 v[52:53], v[52:53], v[132:133], v[196:197]
	v_pk_fma_f32 v[54:55], v[54:55], v[134:135], v[198:199]
	v_pk_fma_f32 v[48:49], v[48:49], v[128:129], v[200:201]
	v_pk_fma_f32 v[50:51], v[50:51], v[130:131], v[202:203]
	v_cvt_pk_bf16_f32 v52, v52, v53
	v_cvt_pk_bf16_f32 v53, v54, v55
	v_cvt_pk_bf16_f32 v54, v48, v49
	v_cvt_pk_bf16_f32 v55, v50, v51
	global_store_dwordx4 v[186:187], v[52:55], off offset:256
	v_lshl_add_u64 v[186:187], v[186:187], 0, s[100:101]
	s_waitcnt vmcnt(10)
	v_pk_fma_f32 v[44:45], v[44:45], v[140:141], v[204:205]
	v_pk_fma_f32 v[46:47], v[46:47], v[142:143], v[206:207]
	v_pk_fma_f32 v[40:41], v[40:41], v[136:137], v[208:209]
	v_pk_fma_f32 v[42:43], v[42:43], v[138:139], v[210:211]
	v_cvt_pk_bf16_f32 v44, v44, v45
	v_cvt_pk_bf16_f32 v45, v46, v47
	v_cvt_pk_bf16_f32 v46, v40, v41
	v_cvt_pk_bf16_f32 v47, v42, v43
	global_store_dwordx4 v[186:187], v[44:47], off
	s_waitcnt vmcnt(8)
	v_pk_fma_f32 v[36:37], v[36:37], v[132:133], v[212:213]
	v_pk_fma_f32 v[38:39], v[38:39], v[134:135], v[214:215]
	v_pk_fma_f32 v[32:33], v[32:33], v[128:129], v[216:217]
	v_pk_fma_f32 v[34:35], v[34:35], v[130:131], v[218:219]
	v_cvt_pk_bf16_f32 v36, v36, v37
	v_cvt_pk_bf16_f32 v37, v38, v39
	v_cvt_pk_bf16_f32 v38, v32, v33
	v_cvt_pk_bf16_f32 v39, v34, v35
	global_store_dwordx4 v[186:187], v[36:39], off offset:256
	v_lshl_add_u64 v[186:187], v[186:187], 0, s[100:101]
	s_waitcnt vmcnt(6)
	v_pk_fma_f32 v[28:29], v[28:29], v[140:141], v[220:221]
	v_pk_fma_f32 v[30:31], v[30:31], v[142:143], v[222:223]
	v_pk_fma_f32 v[24:25], v[24:25], v[136:137], v[224:225]
	v_pk_fma_f32 v[26:27], v[26:27], v[138:139], v[226:227]
	v_cvt_pk_bf16_f32 v28, v28, v29
	v_cvt_pk_bf16_f32 v29, v30, v31
	v_cvt_pk_bf16_f32 v30, v24, v25
	v_cvt_pk_bf16_f32 v31, v26, v27
	global_store_dwordx4 v[186:187], v[28:31], off
	s_waitcnt vmcnt(4)
	v_pk_fma_f32 v[20:21], v[20:21], v[132:133], v[238:239]
	v_pk_fma_f32 v[22:23], v[22:23], v[134:135], v[240:241]
	v_pk_fma_f32 v[16:17], v[16:17], v[128:129], v[242:243]
	v_pk_fma_f32 v[18:19], v[18:19], v[130:131], v[244:245]
	v_cvt_pk_bf16_f32 v20, v20, v21
	v_cvt_pk_bf16_f32 v21, v22, v23
	v_cvt_pk_bf16_f32 v22, v16, v17
	v_cvt_pk_bf16_f32 v23, v18, v19
	global_store_dwordx4 v[186:187], v[20:23], off offset:256
	v_lshl_add_u64 v[186:187], v[186:187], 0, s[100:101]
	s_waitcnt vmcnt(2)
	v_pk_fma_f32 v[12:13], v[12:13], v[140:141], v[246:247]
	v_pk_fma_f32 v[14:15], v[14:15], v[142:143], v[248:249]
	v_pk_fma_f32 v[8:9], v[8:9], v[136:137], v[252:253]
	v_pk_fma_f32 v[10:11], v[10:11], v[138:139], v[254:255]
	v_cvt_pk_bf16_f32 v12, v12, v13
	v_cvt_pk_bf16_f32 v13, v14, v15
	v_cvt_pk_bf16_f32 v14, v8, v9
	v_cvt_pk_bf16_f32 v15, v10, v11
	global_store_dwordx4 v[186:187], v[12:15], off
	s_waitcnt vmcnt(0)
	v_pk_fma_f32 v[4:5], v[4:5], v[132:133], v[160:161]
	v_pk_fma_f32 v[6:7], v[6:7], v[134:135], v[162:163]
	v_pk_fma_f32 v[0:1], v[0:1], v[128:129], v[174:175]
	v_pk_fma_f32 v[2:3], v[2:3], v[130:131], v[176:177]
	v_cvt_pk_bf16_f32 v4, v4, v5
	v_cvt_pk_bf16_f32 v5, v6, v7
	v_cvt_pk_bf16_f32 v6, v0, v1
	v_cvt_pk_bf16_f32 v7, v2, v3
	global_store_dwordx4 v[186:187], v[4:7], off offset:256
	s_cbranch_vccnz .LBB0_1123
	s_andn2_b64 vcc, exec, s[18:19]
	s_cbranch_vccnz .LBB0_1122
	s_barrier
	s_branch .LBB0_1122
